# unit boundary: first load segment LDS reads issued before the tile-scheduler arithmetic, trailing half offset barrier moved after that arithmetic
# baseline (speedup 1.0000x reference)
.LBB0_140:
	s_cmp_eq_u32 s82, 0
	s_cbranch_scc1 .Lnr_p1
	v_add_u32_e32 v28, 0x10000, v83
	v_add_u32_e32 v80, 0x14000, v83
	ds_read_b128 v[16:19], v28
	ds_read_b128 v[20:23], v28 offset:1024
	ds_read_b128 v[24:27], v28 offset:2048
	ds_read_b128 v[28:31], v28 offset:3072
	ds_read_b128 v[152:155], v80
	ds_read_b128 v[160:163], v80 offset:1024
	ds_read_b128 v[168:171], v80 offset:2048
	ds_read_b128 v[176:179], v80 offset:3072
	ds_read_b128 v[192:195], v245
	ds_read_b128 v[196:199], v245 offset:1024
	ds_read_b128 v[200:203], v245 offset:2048
	ds_read_b128 v[204:207], v245 offset:3072
	ds_read_b128 v[220:223], v245 offset:4096
	ds_read_b128 v[224:227], v245 offset:5120
	ds_read_b128 v[228:231], v245 offset:6144
	ds_read_b128 v[246:249], v245 offset:7168

.Lpeel_p1:
	s_waitcnt lgkmcnt(0)
	s_cmp_eq_u32 s101, 0
	s_cbranch_scc1 .Lnb_p1
	s_barrier
.Lnb_p1:
	s_add_i32 s7, s4, 0xfff84000
	s_cmp_eq_u32 s6, 28
	s_cselect_b32 s17, s0, s7
	s_cselect_b32 s16, s1, s5
	s_or_b32 s7, s17, 0x4000
	s_mov_b32 m0, s79
	s_nop 0
	buffer_load_dwordx4 v242, s[24:27], s4 offen lds
	s_nop 0
	s_mov_b32 m0, s83
	s_nop 0
	buffer_load_dwordx4 v243, s[24:27], s4 offen lds
	s_waitcnt vmcnt(24)
	s_waitcnt lgkmcnt(0)
	s_barrier
	s_setprio 1
	s_waitcnt lgkmcnt(7)
	v_mfma_f32_16x16x32_bf16 v[180:183], v[16:19], v[192:195], 0
	v_mfma_f32_16x16x32_bf16 v[164:167], v[24:27], v[192:195], 0
	s_waitcnt lgkmcnt(5)
	v_mfma_f32_16x16x32_bf16 v[148:151], v[16:19], v[200:203], 0
	v_mfma_f32_16x16x32_bf16 v[140:143], v[24:27], v[200:203], 0
	s_waitcnt lgkmcnt(3)
	v_mfma_f32_16x16x32_bf16 v[132:135], v[16:19], v[220:223], 0
	v_mfma_f32_16x16x32_bf16 v[124:127], v[24:27], v[220:223], 0
	s_waitcnt lgkmcnt(1)
	v_mfma_f32_16x16x32_bf16 v[116:119], v[16:19], v[228:231], 0
	v_mfma_f32_16x16x32_bf16 v[108:111], v[24:27], v[228:231], 0
	v_mfma_f32_16x16x32_bf16 v[180:183], v[20:23], v[196:199], v[180:183]
	v_mfma_f32_16x16x32_bf16 v[164:167], v[28:31], v[196:199], v[164:167]
	v_mfma_f32_16x16x32_bf16 v[148:151], v[20:23], v[204:207], v[148:151]
	v_mfma_f32_16x16x32_bf16 v[140:143], v[28:31], v[204:207], v[140:143]
	v_mfma_f32_16x16x32_bf16 v[132:135], v[20:23], v[224:227], v[132:135]
	v_mfma_f32_16x16x32_bf16 v[124:127], v[28:31], v[224:227], v[124:127]
	s_waitcnt lgkmcnt(0)
	v_mfma_f32_16x16x32_bf16 v[116:119], v[20:23], v[246:249], v[116:119]
	v_mfma_f32_16x16x32_bf16 v[108:111], v[28:31], v[246:249], v[108:111]
	s_setprio 0
	s_setprio 1
	v_mfma_f32_16x16x32_bf16 v[172:175], v[152:155], v[192:195], 0
	v_mfma_f32_16x16x32_bf16 v[156:159], v[168:171], v[192:195], 0
	v_mfma_f32_16x16x32_bf16 v[144:147], v[152:155], v[200:203], 0
	v_mfma_f32_16x16x32_bf16 v[136:139], v[168:171], v[200:203], 0
	v_mfma_f32_16x16x32_bf16 v[128:131], v[152:155], v[220:223], 0
	v_mfma_f32_16x16x32_bf16 v[120:123], v[168:171], v[220:223], 0
	v_mfma_f32_16x16x32_bf16 v[112:115], v[152:155], v[228:231], 0
	v_mfma_f32_16x16x32_bf16 v[104:107], v[168:171], v[228:231], 0
	v_mfma_f32_16x16x32_bf16 v[172:175], v[160:163], v[196:199], v[172:175]
	v_mfma_f32_16x16x32_bf16 v[156:159], v[176:179], v[196:199], v[156:159]
	v_mfma_f32_16x16x32_bf16 v[144:147], v[160:163], v[204:207], v[144:147]
	v_mfma_f32_16x16x32_bf16 v[136:139], v[176:179], v[204:207], v[136:139]
	v_mfma_f32_16x16x32_bf16 v[128:131], v[160:163], v[224:227], v[128:131]
	v_mfma_f32_16x16x32_bf16 v[120:123], v[176:179], v[224:227], v[120:123]
	v_mfma_f32_16x16x32_bf16 v[112:115], v[160:163], v[246:249], v[112:115]
	v_mfma_f32_16x16x32_bf16 v[104:107], v[176:179], v[246:249], v[104:107]
	s_setprio 0
	s_barrier
	ds_read_b128 v[192:195], v245 offset:16384
	ds_read_b128 v[196:199], v245 offset:17408
	ds_read_b128 v[200:203], v245 offset:18432
	ds_read_b128 v[204:207], v245 offset:19456
	ds_read_b128 v[220:223], v245 offset:20480
	ds_read_b128 v[224:227], v245 offset:21504
	ds_read_b128 v[228:231], v245 offset:22528
	ds_read_b128 v[246:249], v245 offset:23552
	s_mov_b32 m0, s51
	s_nop 0
	buffer_load_dwordx4 v242, s[56:59], s16 offen lds
	s_add_i32 s18, s16, 0x80000
	s_mov_b32 m0, s52
	s_nop 0
	buffer_load_dwordx4 v243, s[56:59], s16 offen lds
	s_nop 0
	s_mov_b32 m0, s53
	s_nop 0
	buffer_load_dwordx4 v242, s[56:59], s18 offen lds
	s_nop 0
	s_mov_b32 m0, s55
	s_nop 0
	buffer_load_dwordx4 v243, s[56:59], s18 offen lds
	s_nop 0
	s_mov_b32 m0, s31
	s_nop 0
	buffer_load_dwordx4 v242, s[24:27], s17 offen lds
	s_nop 0
	s_mov_b32 m0, s68
	s_nop 0
	buffer_load_dwordx4 v243, s[24:27], s17 offen lds
	s_waitcnt vmcnt(24)
	s_waitcnt lgkmcnt(0)
	s_barrier
	s_setprio 1
	s_waitcnt lgkmcnt(7)
	v_mfma_f32_16x16x32_bf16 v[76:79], v[16:19], v[192:195], 0
	v_mfma_f32_16x16x32_bf16 v[68:71], v[24:27], v[192:195], 0
	s_waitcnt lgkmcnt(5)
	v_mfma_f32_16x16x32_bf16 v[60:63], v[16:19], v[200:203], 0
	v_mfma_f32_16x16x32_bf16 v[52:55], v[24:27], v[200:203], 0
	s_waitcnt lgkmcnt(3)
	v_mfma_f32_16x16x32_bf16 v[44:47], v[16:19], v[220:223], 0
	v_mfma_f32_16x16x32_bf16 v[36:39], v[24:27], v[220:223], 0
	s_waitcnt lgkmcnt(1)
	v_mfma_f32_16x16x32_bf16 v[12:15], v[16:19], v[228:231], 0
	v_mfma_f32_16x16x32_bf16 v[4:7], v[24:27], v[228:231], 0
	v_mfma_f32_16x16x32_bf16 v[76:79], v[20:23], v[196:199], v[76:79]
	v_mfma_f32_16x16x32_bf16 v[68:71], v[28:31], v[196:199], v[68:71]
	v_mfma_f32_16x16x32_bf16 v[60:63], v[20:23], v[204:207], v[60:63]
	v_mfma_f32_16x16x32_bf16 v[52:55], v[28:31], v[204:207], v[52:55]
	v_mfma_f32_16x16x32_bf16 v[44:47], v[20:23], v[224:227], v[44:47]
	v_mfma_f32_16x16x32_bf16 v[36:39], v[28:31], v[224:227], v[36:39]
	s_waitcnt lgkmcnt(0)
	v_mfma_f32_16x16x32_bf16 v[12:15], v[20:23], v[246:249], v[12:15]
	v_mfma_f32_16x16x32_bf16 v[4:7], v[28:31], v[246:249], v[4:7]
	s_setprio 0
	s_setprio 1
	v_mfma_f32_16x16x32_bf16 v[40:43], v[152:155], v[220:223], 0
	v_mfma_f32_16x16x32_bf16 v[32:35], v[168:171], v[220:223], 0
	v_mfma_f32_16x16x32_bf16 v[8:11], v[152:155], v[228:231], 0
	v_mfma_f32_16x16x32_bf16 v[0:3], v[168:171], v[228:231], 0
	v_mfma_f32_16x16x32_bf16 v[16:19], v[152:155], v[192:195], 0
	v_mfma_f32_16x16x32_bf16 v[20:23], v[168:171], v[192:195], 0
	v_mfma_f32_16x16x32_bf16 v[24:27], v[152:155], v[200:203], 0
	v_mfma_f32_16x16x32_bf16 v[28:31], v[168:171], v[200:203], 0
	v_mfma_f32_16x16x32_bf16 v[40:43], v[160:163], v[224:227], v[40:43]
	v_mfma_f32_16x16x32_bf16 v[32:35], v[176:179], v[224:227], v[32:35]
	v_mfma_f32_16x16x32_bf16 v[8:11], v[160:163], v[246:249], v[8:11]
	v_mfma_f32_16x16x32_bf16 v[0:3], v[176:179], v[246:249], v[0:3]
	v_mfma_f32_16x16x32_bf16 v[16:19], v[160:163], v[196:199], v[16:19]
	v_mfma_f32_16x16x32_bf16 v[20:23], v[176:179], v[196:199], v[20:23]
	v_mfma_f32_16x16x32_bf16 v[24:27], v[160:163], v[204:207], v[24:27]
	v_mfma_f32_16x16x32_bf16 v[28:31], v[176:179], v[204:207], v[28:31]
	s_setprio 0
	s_barrier
	v_add_u32_e32 v72, 0x18000, v83
	v_add_u32_e32 v80, 0x1c000, v83
	ds_read_b128 v[48:51], v72
	ds_read_b128 v[56:59], v72 offset:1024
	ds_read_b128 v[64:67], v72 offset:2048
	ds_read_b128 v[72:75], v72 offset:3072
	ds_read_b128 v[152:155], v80
	ds_read_b128 v[160:163], v80 offset:1024
	ds_read_b128 v[168:171], v80 offset:2048
	ds_read_b128 v[176:179], v80 offset:3072
	ds_read_b128 v[192:195], v245 offset:32768
	ds_read_b128 v[196:199], v245 offset:33792
	ds_read_b128 v[200:203], v245 offset:34816
	ds_read_b128 v[204:207], v245 offset:35840
	ds_read_b128 v[220:223], v245 offset:36864
	ds_read_b128 v[224:227], v245 offset:37888
	ds_read_b128 v[228:231], v245 offset:38912
	ds_read_b128 v[246:249], v245 offset:39936
	s_add_i32 s17, s17, 0x80000
	s_mov_b32 m0, s69
	s_nop 0
	buffer_load_dwordx4 v242, s[24:27], s17 offen lds
	s_nop 0
	s_mov_b32 m0, s70
	s_nop 0
	buffer_load_dwordx4 v243, s[24:27], s17 offen lds
	s_waitcnt vmcnt(8)
	s_waitcnt lgkmcnt(0)
	s_barrier
	s_setprio 1
	s_waitcnt lgkmcnt(7)
	v_mfma_f32_16x16x32_bf16 v[180:183], v[48:51], v[192:195], v[180:183]
	v_mfma_f32_16x16x32_bf16 v[164:167], v[64:67], v[192:195], v[164:167]
	s_waitcnt lgkmcnt(5)
	v_mfma_f32_16x16x32_bf16 v[148:151], v[48:51], v[200:203], v[148:151]
	v_mfma_f32_16x16x32_bf16 v[140:143], v[64:67], v[200:203], v[140:143]
	s_waitcnt lgkmcnt(3)
	v_mfma_f32_16x16x32_bf16 v[132:135], v[48:51], v[220:223], v[132:135]
	v_mfma_f32_16x16x32_bf16 v[124:127], v[64:67], v[220:223], v[124:127]
	s_waitcnt lgkmcnt(1)
	v_mfma_f32_16x16x32_bf16 v[116:119], v[48:51], v[228:231], v[116:119]
	v_mfma_f32_16x16x32_bf16 v[108:111], v[64:67], v[228:231], v[108:111]
	v_mfma_f32_16x16x32_bf16 v[180:183], v[56:59], v[196:199], v[180:183]
	v_mfma_f32_16x16x32_bf16 v[164:167], v[72:75], v[196:199], v[164:167]
	v_mfma_f32_16x16x32_bf16 v[148:151], v[56:59], v[204:207], v[148:151]
	v_mfma_f32_16x16x32_bf16 v[140:143], v[72:75], v[204:207], v[140:143]
	v_mfma_f32_16x16x32_bf16 v[132:135], v[56:59], v[224:227], v[132:135]
	v_mfma_f32_16x16x32_bf16 v[124:127], v[72:75], v[224:227], v[124:127]
	s_waitcnt lgkmcnt(0)
	v_mfma_f32_16x16x32_bf16 v[116:119], v[56:59], v[246:249], v[116:119]
	v_mfma_f32_16x16x32_bf16 v[108:111], v[72:75], v[246:249], v[108:111]
	s_setprio 0
	s_setprio 1
	v_mfma_f32_16x16x32_bf16 v[172:175], v[152:155], v[192:195], v[172:175]
	v_mfma_f32_16x16x32_bf16 v[156:159], v[168:171], v[192:195], v[156:159]
	v_mfma_f32_16x16x32_bf16 v[144:147], v[152:155], v[200:203], v[144:147]
	v_mfma_f32_16x16x32_bf16 v[136:139], v[168:171], v[200:203], v[136:139]
	v_mfma_f32_16x16x32_bf16 v[128:131], v[152:155], v[220:223], v[128:131]
	v_mfma_f32_16x16x32_bf16 v[120:123], v[168:171], v[220:223], v[120:123]
	v_mfma_f32_16x16x32_bf16 v[112:115], v[152:155], v[228:231], v[112:115]
	v_mfma_f32_16x16x32_bf16 v[104:107], v[168:171], v[228:231], v[104:107]
	v_mfma_f32_16x16x32_bf16 v[172:175], v[160:163], v[196:199], v[172:175]
	v_mfma_f32_16x16x32_bf16 v[156:159], v[176:179], v[196:199], v[156:159]
	v_mfma_f32_16x16x32_bf16 v[144:147], v[160:163], v[204:207], v[144:147]
	v_mfma_f32_16x16x32_bf16 v[136:139], v[176:179], v[204:207], v[136:139]
	v_mfma_f32_16x16x32_bf16 v[128:131], v[160:163], v[224:227], v[128:131]
	v_mfma_f32_16x16x32_bf16 v[120:123], v[176:179], v[224:227], v[120:123]
	v_mfma_f32_16x16x32_bf16 v[112:115], v[160:163], v[246:249], v[112:115]
	v_mfma_f32_16x16x32_bf16 v[104:107], v[176:179], v[246:249], v[104:107]
	s_setprio 0
	s_barrier
	ds_read_b128 v[192:195], v245 offset:49152
	ds_read_b128 v[196:199], v245 offset:50176
	ds_read_b128 v[200:203], v245 offset:51200
	ds_read_b128 v[204:207], v245 offset:52224
	ds_read_b128 v[220:223], v245 offset:53248
	ds_read_b128 v[224:227], v245 offset:54272
	ds_read_b128 v[228:231], v245 offset:55296
	ds_read_b128 v[246:249], v245 offset:56320
	s_or_b32 s17, s16, 0x4000
	s_mov_b32 m0, s73
	s_nop 0
	buffer_load_dwordx4 v242, s[56:59], s17 offen lds
	s_add_i32 s16, s16, 0x84000
	s_mov_b32 m0, s74
	s_nop 0
	buffer_load_dwordx4 v243, s[56:59], s17 offen lds
	s_nop 0
	s_mov_b32 m0, s77
	s_nop 0
	buffer_load_dwordx4 v242, s[56:59], s16 offen lds
	s_nop 0
	s_mov_b32 m0, s78
	s_nop 0
	buffer_load_dwordx4 v243, s[56:59], s16 offen lds
	s_nop 0
	s_mov_b32 m0, s75
	s_nop 0
	buffer_load_dwordx4 v242, s[24:27], s7 offen lds
	s_nop 0
	s_mov_b32 m0, s76
	s_nop 0
	buffer_load_dwordx4 v243, s[24:27], s7 offen lds
	s_waitcnt vmcnt(8)
	s_waitcnt lgkmcnt(0)
	s_barrier
	s_setprio 1
	s_waitcnt lgkmcnt(7)
	v_mfma_f32_16x16x32_bf16 v[76:79], v[48:51], v[192:195], v[76:79]
	v_mfma_f32_16x16x32_bf16 v[68:71], v[64:67], v[192:195], v[68:71]
	s_waitcnt lgkmcnt(5)
	v_mfma_f32_16x16x32_bf16 v[60:63], v[48:51], v[200:203], v[60:63]
	v_mfma_f32_16x16x32_bf16 v[52:55], v[64:67], v[200:203], v[52:55]
	s_waitcnt lgkmcnt(3)
	v_mfma_f32_16x16x32_bf16 v[44:47], v[48:51], v[220:223], v[44:47]
	v_mfma_f32_16x16x32_bf16 v[36:39], v[64:67], v[220:223], v[36:39]
	s_waitcnt lgkmcnt(1)
	v_mfma_f32_16x16x32_bf16 v[12:15], v[48:51], v[228:231], v[12:15]
	v_mfma_f32_16x16x32_bf16 v[4:7], v[64:67], v[228:231], v[4:7]
	v_mfma_f32_16x16x32_bf16 v[76:79], v[56:59], v[196:199], v[76:79]
	v_mfma_f32_16x16x32_bf16 v[68:71], v[72:75], v[196:199], v[68:71]
	v_mfma_f32_16x16x32_bf16 v[60:63], v[56:59], v[204:207], v[60:63]
	v_mfma_f32_16x16x32_bf16 v[52:55], v[72:75], v[204:207], v[52:55]
	v_mfma_f32_16x16x32_bf16 v[44:47], v[56:59], v[224:227], v[44:47]
	v_mfma_f32_16x16x32_bf16 v[36:39], v[72:75], v[224:227], v[36:39]
	s_waitcnt lgkmcnt(0)
	v_mfma_f32_16x16x32_bf16 v[12:15], v[56:59], v[246:249], v[12:15]
	v_mfma_f32_16x16x32_bf16 v[4:7], v[72:75], v[246:249], v[4:7]
	s_setprio 0
	s_setprio 1
	v_mfma_f32_16x16x32_bf16 v[16:19], v[152:155], v[192:195], v[16:19]
	v_mfma_f32_16x16x32_bf16 v[72:75], v[160:163], v[196:199], v[16:19]
	v_mfma_f32_16x16x32_bf16 v[16:19], v[168:171], v[192:195], v[20:23]
	v_mfma_f32_16x16x32_bf16 v[64:67], v[176:179], v[196:199], v[16:19]
	v_mfma_f32_16x16x32_bf16 v[16:19], v[152:155], v[200:203], v[24:27]
	v_mfma_f32_16x16x32_bf16 v[56:59], v[160:163], v[204:207], v[16:19]
	v_mfma_f32_16x16x32_bf16 v[16:19], v[168:171], v[200:203], v[28:31]
	v_mfma_f32_16x16x32_bf16 v[48:51], v[176:179], v[204:207], v[16:19]
	v_mfma_f32_16x16x32_bf16 v[16:19], v[152:155], v[220:223], v[40:43]
	v_mfma_f32_16x16x32_bf16 v[40:43], v[160:163], v[224:227], v[16:19]
	v_mfma_f32_16x16x32_bf16 v[16:19], v[168:171], v[220:223], v[32:35]
	v_mfma_f32_16x16x32_bf16 v[8:11], v[152:155], v[228:231], v[8:11]
	v_mfma_f32_16x16x32_bf16 v[0:3], v[168:171], v[228:231], v[0:3]
	v_mfma_f32_16x16x32_bf16 v[32:35], v[176:179], v[224:227], v[16:19]
	v_mfma_f32_16x16x32_bf16 v[8:11], v[160:163], v[246:249], v[8:11]
	v_mfma_f32_16x16x32_bf16 v[0:3], v[176:179], v[246:249], v[0:3]
	s_setprio 0
	s_barrier
	s_add_i32 s6, s6, 2
	s_add_i32 s4, s4, 0x8000
	s_add_i32 s5, s5, 0x8000

.LBB0_367:
	v_readlane_b32 s0, v254, 23
	v_readlane_b32 s1, v254, 24
	s_mov_b32 s101, 0
	s_andn2_b64 vcc, exec, s[0:1]
	s_cbranch_vccnz .LBB0_138
	s_mov_b32 s101, 1
	s_branch .LBB0_138

.LBB0_684:
	s_cmp_eq_u32 s90, 0
	s_cbranch_scc1 .Lnr_p4
	v_add_u32_e32 v156, 0x10000, v222
	v_add_u32_e32 v180, 0x14000, v222
	ds_read_b128 v[128:131], v156
	ds_read_b128 v[140:143], v156 offset:1024
	ds_read_b128 v[152:155], v156 offset:2048
	ds_read_b128 v[156:159], v156 offset:3072
	ds_read_b128 v[168:171], v180
	ds_read_b128 v[172:175], v180 offset:1024
	ds_read_b128 v[176:179], v180 offset:2048
	ds_read_b128 v[180:183], v180 offset:3072
	ds_read_b128 v[184:187], v223
	ds_read_b128 v[188:191], v223 offset:1024
	ds_read_b128 v[192:195], v223 offset:2048
	ds_read_b128 v[196:199], v223 offset:3072
	ds_read_b128 v[200:203], v223 offset:4096
	ds_read_b128 v[204:207], v223 offset:5120
	ds_read_b128 v[224:227], v223 offset:6144
	ds_read_b128 v[228:231], v223 offset:7168

.Lnb_p4:
	s_add_i32 s11, s8, 0xfff84000
	s_cmp_eq_u32 s10, 28
	s_cselect_b32 s13, s6, s11
	s_cselect_b32 s12, s7, s9
	s_or_b32 s11, s13, 0x4000
	s_mov_b32 m0, s89
	s_nop 0
	buffer_load_dwordx4 v220, s[64:67], s8 offen lds
	s_nop 0
	s_mov_b32 m0, s91
	s_nop 0
	buffer_load_dwordx4 v221, s[64:67], s8 offen lds
	s_waitcnt vmcnt(24)
	s_waitcnt lgkmcnt(0)
	s_barrier
	s_setprio 1
	s_waitcnt lgkmcnt(7)
	v_mfma_f32_16x16x32_bf16 v[164:167], v[128:131], v[184:187], 0
	v_mfma_f32_16x16x32_bf16 v[160:163], v[152:155], v[184:187], 0
	s_waitcnt lgkmcnt(5)
	v_mfma_f32_16x16x32_bf16 v[136:139], v[128:131], v[192:195], 0
	v_mfma_f32_16x16x32_bf16 v[132:135], v[152:155], v[192:195], 0
	s_waitcnt lgkmcnt(3)
	v_mfma_f32_16x16x32_bf16 v[116:119], v[128:131], v[200:203], 0
	v_mfma_f32_16x16x32_bf16 v[112:115], v[152:155], v[200:203], 0
	s_waitcnt lgkmcnt(1)
	v_mfma_f32_16x16x32_bf16 v[76:79], v[128:131], v[224:227], 0
	v_mfma_f32_16x16x32_bf16 v[72:75], v[152:155], v[224:227], 0
	v_mfma_f32_16x16x32_bf16 v[164:167], v[140:143], v[188:191], v[164:167]
	v_mfma_f32_16x16x32_bf16 v[160:163], v[156:159], v[188:191], v[160:163]
	v_mfma_f32_16x16x32_bf16 v[136:139], v[140:143], v[196:199], v[136:139]
	v_mfma_f32_16x16x32_bf16 v[132:135], v[156:159], v[196:199], v[132:135]
	v_mfma_f32_16x16x32_bf16 v[116:119], v[140:143], v[204:207], v[116:119]
	v_mfma_f32_16x16x32_bf16 v[112:115], v[156:159], v[204:207], v[112:115]
	s_waitcnt lgkmcnt(0)
	v_mfma_f32_16x16x32_bf16 v[76:79], v[140:143], v[228:231], v[76:79]
	v_mfma_f32_16x16x32_bf16 v[72:75], v[156:159], v[228:231], v[72:75]
	s_setprio 0
	s_setprio 1
	v_mfma_f32_16x16x32_bf16 v[148:151], v[168:171], v[184:187], 0
	v_mfma_f32_16x16x32_bf16 v[144:147], v[176:179], v[184:187], 0
	v_mfma_f32_16x16x32_bf16 v[124:127], v[168:171], v[192:195], 0
	v_mfma_f32_16x16x32_bf16 v[120:123], v[176:179], v[192:195], 0
	v_mfma_f32_16x16x32_bf16 v[108:111], v[168:171], v[200:203], 0
	v_mfma_f32_16x16x32_bf16 v[104:107], v[176:179], v[200:203], 0
	v_mfma_f32_16x16x32_bf16 v[68:71], v[168:171], v[224:227], 0
	v_mfma_f32_16x16x32_bf16 v[64:67], v[176:179], v[224:227], 0
	v_mfma_f32_16x16x32_bf16 v[148:151], v[172:175], v[188:191], v[148:151]
	v_mfma_f32_16x16x32_bf16 v[144:147], v[180:183], v[188:191], v[144:147]
	v_mfma_f32_16x16x32_bf16 v[124:127], v[172:175], v[196:199], v[124:127]
	v_mfma_f32_16x16x32_bf16 v[120:123], v[180:183], v[196:199], v[120:123]
	v_mfma_f32_16x16x32_bf16 v[108:111], v[172:175], v[204:207], v[108:111]
	v_mfma_f32_16x16x32_bf16 v[104:107], v[180:183], v[204:207], v[104:107]
	v_mfma_f32_16x16x32_bf16 v[68:71], v[172:175], v[228:231], v[68:71]
	v_mfma_f32_16x16x32_bf16 v[64:67], v[180:183], v[228:231], v[64:67]
	s_setprio 0
	s_barrier
	ds_read_b128 v[184:187], v223 offset:16384
	ds_read_b128 v[188:191], v223 offset:17408
	ds_read_b128 v[192:195], v223 offset:18432
	ds_read_b128 v[196:199], v223 offset:19456
	ds_read_b128 v[200:203], v223 offset:20480
	ds_read_b128 v[204:207], v223 offset:21504
	ds_read_b128 v[224:227], v223 offset:22528
	ds_read_b128 v[228:231], v223 offset:23552
	s_mov_b32 m0, s55
	s_nop 0
	buffer_load_dwordx4 v220, s[48:51], s12 offen lds
	s_add_i32 s14, s12, 0x80000
	s_mov_b32 m0, s76
	s_nop 0
	buffer_load_dwordx4 v221, s[48:51], s12 offen lds
	s_nop 0
	s_mov_b32 m0, s77
	s_nop 0
	buffer_load_dwordx4 v220, s[48:51], s14 offen lds
	s_nop 0
	s_mov_b32 m0, s78
	s_nop 0
	buffer_load_dwordx4 v221, s[48:51], s14 offen lds
	s_nop 0
	s_mov_b32 m0, s31
	s_nop 0
	buffer_load_dwordx4 v220, s[64:67], s13 offen lds
	s_nop 0
	s_mov_b32 m0, s79
	s_nop 0
	buffer_load_dwordx4 v221, s[64:67], s13 offen lds
	s_waitcnt vmcnt(24)
	s_waitcnt lgkmcnt(0)
	s_barrier
	s_setprio 1
	s_waitcnt lgkmcnt(7)
	v_mfma_f32_16x16x32_bf16 v[60:63], v[128:131], v[184:187], 0
	v_mfma_f32_16x16x32_bf16 v[56:59], v[152:155], v[184:187], 0
	s_waitcnt lgkmcnt(5)
	v_mfma_f32_16x16x32_bf16 v[44:47], v[128:131], v[192:195], 0
	v_mfma_f32_16x16x32_bf16 v[40:43], v[152:155], v[192:195], 0
	s_waitcnt lgkmcnt(3)
	v_mfma_f32_16x16x32_bf16 v[28:31], v[128:131], v[200:203], 0
	v_mfma_f32_16x16x32_bf16 v[24:27], v[152:155], v[200:203], 0
	s_waitcnt lgkmcnt(1)
	v_mfma_f32_16x16x32_bf16 v[12:15], v[128:131], v[224:227], 0
	v_mfma_f32_16x16x32_bf16 v[8:11], v[152:155], v[224:227], 0
	v_mfma_f32_16x16x32_bf16 v[60:63], v[140:143], v[188:191], v[60:63]
	v_mfma_f32_16x16x32_bf16 v[56:59], v[156:159], v[188:191], v[56:59]
	v_mfma_f32_16x16x32_bf16 v[44:47], v[140:143], v[196:199], v[44:47]
	v_mfma_f32_16x16x32_bf16 v[40:43], v[156:159], v[196:199], v[40:43]
	v_mfma_f32_16x16x32_bf16 v[28:31], v[140:143], v[204:207], v[28:31]
	v_mfma_f32_16x16x32_bf16 v[24:27], v[156:159], v[204:207], v[24:27]
	s_waitcnt lgkmcnt(0)
	v_mfma_f32_16x16x32_bf16 v[12:15], v[140:143], v[228:231], v[12:15]
	v_mfma_f32_16x16x32_bf16 v[8:11], v[156:159], v[228:231], v[8:11]
	s_setprio 0
	s_setprio 1
	v_mfma_f32_16x16x32_bf16 v[52:55], v[168:171], v[184:187], 0
	v_mfma_f32_16x16x32_bf16 v[48:51], v[176:179], v[184:187], 0
	v_mfma_f32_16x16x32_bf16 v[36:39], v[168:171], v[192:195], 0
	v_mfma_f32_16x16x32_bf16 v[32:35], v[176:179], v[192:195], 0
	v_mfma_f32_16x16x32_bf16 v[20:23], v[168:171], v[200:203], 0
	v_mfma_f32_16x16x32_bf16 v[16:19], v[176:179], v[200:203], 0
	v_mfma_f32_16x16x32_bf16 v[4:7], v[168:171], v[224:227], 0
	v_mfma_f32_16x16x32_bf16 v[0:3], v[176:179], v[224:227], 0
	v_mfma_f32_16x16x32_bf16 v[52:55], v[172:175], v[188:191], v[52:55]
	v_mfma_f32_16x16x32_bf16 v[48:51], v[180:183], v[188:191], v[48:51]
	v_mfma_f32_16x16x32_bf16 v[36:39], v[172:175], v[196:199], v[36:39]
	v_mfma_f32_16x16x32_bf16 v[32:35], v[180:183], v[196:199], v[32:35]
	v_mfma_f32_16x16x32_bf16 v[20:23], v[172:175], v[204:207], v[20:23]
	v_mfma_f32_16x16x32_bf16 v[16:19], v[180:183], v[204:207], v[16:19]
	v_mfma_f32_16x16x32_bf16 v[4:7], v[172:175], v[228:231], v[4:7]
	v_mfma_f32_16x16x32_bf16 v[0:3], v[180:183], v[228:231], v[0:3]
	s_setprio 0
	s_barrier
	v_add_u32_e32 v156, 0x18000, v222
	v_add_u32_e32 v180, 0x1c000, v222
	ds_read_b128 v[128:131], v156
	ds_read_b128 v[140:143], v156 offset:1024
	ds_read_b128 v[152:155], v156 offset:2048
	ds_read_b128 v[156:159], v156 offset:3072
	ds_read_b128 v[168:171], v180
	ds_read_b128 v[172:175], v180 offset:1024
	ds_read_b128 v[176:179], v180 offset:2048
	ds_read_b128 v[180:183], v180 offset:3072
	ds_read_b128 v[184:187], v223 offset:32768
	ds_read_b128 v[188:191], v223 offset:33792
	ds_read_b128 v[192:195], v223 offset:34816
	ds_read_b128 v[196:199], v223 offset:35840
	ds_read_b128 v[200:203], v223 offset:36864
	ds_read_b128 v[204:207], v223 offset:37888
	ds_read_b128 v[224:227], v223 offset:38912
	ds_read_b128 v[228:231], v223 offset:39936
	s_add_i32 s13, s13, 0x80000
	s_mov_b32 m0, s82
	s_nop 0
	buffer_load_dwordx4 v220, s[64:67], s13 offen lds
	s_nop 0
	s_mov_b32 m0, s83
	s_nop 0
	buffer_load_dwordx4 v221, s[64:67], s13 offen lds
	s_waitcnt vmcnt(8)
	s_waitcnt lgkmcnt(0)
	s_barrier
	s_setprio 1
	s_waitcnt lgkmcnt(7)
	v_mfma_f32_16x16x32_bf16 v[164:167], v[128:131], v[184:187], v[164:167]
	v_mfma_f32_16x16x32_bf16 v[160:163], v[152:155], v[184:187], v[160:163]
	s_waitcnt lgkmcnt(5)
	v_mfma_f32_16x16x32_bf16 v[136:139], v[128:131], v[192:195], v[136:139]
	v_mfma_f32_16x16x32_bf16 v[132:135], v[152:155], v[192:195], v[132:135]
	s_waitcnt lgkmcnt(3)
	v_mfma_f32_16x16x32_bf16 v[116:119], v[128:131], v[200:203], v[116:119]
	v_mfma_f32_16x16x32_bf16 v[112:115], v[152:155], v[200:203], v[112:115]
	s_waitcnt lgkmcnt(1)
	v_mfma_f32_16x16x32_bf16 v[76:79], v[128:131], v[224:227], v[76:79]
	v_mfma_f32_16x16x32_bf16 v[72:75], v[152:155], v[224:227], v[72:75]
	v_mfma_f32_16x16x32_bf16 v[164:167], v[140:143], v[188:191], v[164:167]
	v_mfma_f32_16x16x32_bf16 v[160:163], v[156:159], v[188:191], v[160:163]
	v_mfma_f32_16x16x32_bf16 v[136:139], v[140:143], v[196:199], v[136:139]
	v_mfma_f32_16x16x32_bf16 v[132:135], v[156:159], v[196:199], v[132:135]
	v_mfma_f32_16x16x32_bf16 v[116:119], v[140:143], v[204:207], v[116:119]
	v_mfma_f32_16x16x32_bf16 v[112:115], v[156:159], v[204:207], v[112:115]
	s_waitcnt lgkmcnt(0)
	v_mfma_f32_16x16x32_bf16 v[76:79], v[140:143], v[228:231], v[76:79]
	v_mfma_f32_16x16x32_bf16 v[72:75], v[156:159], v[228:231], v[72:75]
	s_setprio 0
	s_setprio 1
	v_mfma_f32_16x16x32_bf16 v[148:151], v[168:171], v[184:187], v[148:151]
	v_mfma_f32_16x16x32_bf16 v[144:147], v[176:179], v[184:187], v[144:147]
	v_mfma_f32_16x16x32_bf16 v[124:127], v[168:171], v[192:195], v[124:127]
	v_mfma_f32_16x16x32_bf16 v[120:123], v[176:179], v[192:195], v[120:123]
	v_mfma_f32_16x16x32_bf16 v[108:111], v[168:171], v[200:203], v[108:111]
	v_mfma_f32_16x16x32_bf16 v[104:107], v[176:179], v[200:203], v[104:107]
	v_mfma_f32_16x16x32_bf16 v[68:71], v[168:171], v[224:227], v[68:71]
	v_mfma_f32_16x16x32_bf16 v[64:67], v[176:179], v[224:227], v[64:67]
	v_mfma_f32_16x16x32_bf16 v[148:151], v[172:175], v[188:191], v[148:151]
	v_mfma_f32_16x16x32_bf16 v[144:147], v[180:183], v[188:191], v[144:147]
	v_mfma_f32_16x16x32_bf16 v[124:127], v[172:175], v[196:199], v[124:127]
	v_mfma_f32_16x16x32_bf16 v[120:123], v[180:183], v[196:199], v[120:123]
	v_mfma_f32_16x16x32_bf16 v[108:111], v[172:175], v[204:207], v[108:111]
	v_mfma_f32_16x16x32_bf16 v[104:107], v[180:183], v[204:207], v[104:107]
	v_mfma_f32_16x16x32_bf16 v[68:71], v[172:175], v[228:231], v[68:71]
	v_mfma_f32_16x16x32_bf16 v[64:67], v[180:183], v[228:231], v[64:67]
	s_setprio 0
	s_barrier
	ds_read_b128 v[184:187], v223 offset:49152
	ds_read_b128 v[188:191], v223 offset:50176
	ds_read_b128 v[192:195], v223 offset:51200
	ds_read_b128 v[196:199], v223 offset:52224
	ds_read_b128 v[200:203], v223 offset:53248
	ds_read_b128 v[204:207], v223 offset:54272
	ds_read_b128 v[224:227], v223 offset:55296
	ds_read_b128 v[228:231], v223 offset:56320
	s_or_b32 s13, s12, 0x4000
	s_mov_b32 m0, s34
	s_nop 0
	buffer_load_dwordx4 v220, s[48:51], s13 offen lds
	s_add_i32 s12, s12, 0x84000
	s_mov_b32 m0, s84
	s_nop 0
	buffer_load_dwordx4 v221, s[48:51], s13 offen lds
	s_nop 0
	s_mov_b32 m0, s87
	s_nop 0
	buffer_load_dwordx4 v220, s[48:51], s12 offen lds
	s_nop 0
	s_mov_b32 m0, s88
	s_nop 0
	buffer_load_dwordx4 v221, s[48:51], s12 offen lds
	s_nop 0
	s_mov_b32 m0, s85
	s_nop 0
	buffer_load_dwordx4 v220, s[64:67], s11 offen lds
	s_nop 0
	s_mov_b32 m0, s86
	s_nop 0
	buffer_load_dwordx4 v221, s[64:67], s11 offen lds
	s_waitcnt vmcnt(8)
	s_waitcnt lgkmcnt(0)
	s_barrier
	s_setprio 1
	s_waitcnt lgkmcnt(7)
	v_mfma_f32_16x16x32_bf16 v[60:63], v[128:131], v[184:187], v[60:63]
	v_mfma_f32_16x16x32_bf16 v[56:59], v[152:155], v[184:187], v[56:59]
	s_waitcnt lgkmcnt(5)
	v_mfma_f32_16x16x32_bf16 v[44:47], v[128:131], v[192:195], v[44:47]
	v_mfma_f32_16x16x32_bf16 v[40:43], v[152:155], v[192:195], v[40:43]
	s_waitcnt lgkmcnt(3)
	v_mfma_f32_16x16x32_bf16 v[28:31], v[128:131], v[200:203], v[28:31]
	v_mfma_f32_16x16x32_bf16 v[24:27], v[152:155], v[200:203], v[24:27]
	s_waitcnt lgkmcnt(1)
	v_mfma_f32_16x16x32_bf16 v[12:15], v[128:131], v[224:227], v[12:15]
	v_mfma_f32_16x16x32_bf16 v[8:11], v[152:155], v[224:227], v[8:11]
	v_mfma_f32_16x16x32_bf16 v[60:63], v[140:143], v[188:191], v[60:63]
	v_mfma_f32_16x16x32_bf16 v[56:59], v[156:159], v[188:191], v[56:59]
	v_mfma_f32_16x16x32_bf16 v[44:47], v[140:143], v[196:199], v[44:47]
	v_mfma_f32_16x16x32_bf16 v[40:43], v[156:159], v[196:199], v[40:43]
	v_mfma_f32_16x16x32_bf16 v[28:31], v[140:143], v[204:207], v[28:31]
	v_mfma_f32_16x16x32_bf16 v[24:27], v[156:159], v[204:207], v[24:27]
	s_waitcnt lgkmcnt(0)
	v_mfma_f32_16x16x32_bf16 v[12:15], v[140:143], v[228:231], v[12:15]
	v_mfma_f32_16x16x32_bf16 v[8:11], v[156:159], v[228:231], v[8:11]
	s_setprio 0
	s_setprio 1
	v_mfma_f32_16x16x32_bf16 v[52:55], v[168:171], v[184:187], v[52:55]
	v_mfma_f32_16x16x32_bf16 v[48:51], v[176:179], v[184:187], v[48:51]
	v_mfma_f32_16x16x32_bf16 v[36:39], v[168:171], v[192:195], v[36:39]
	v_mfma_f32_16x16x32_bf16 v[32:35], v[176:179], v[192:195], v[32:35]
	v_mfma_f32_16x16x32_bf16 v[20:23], v[168:171], v[200:203], v[20:23]
	v_mfma_f32_16x16x32_bf16 v[16:19], v[176:179], v[200:203], v[16:19]
	v_mfma_f32_16x16x32_bf16 v[4:7], v[168:171], v[224:227], v[4:7]
	v_mfma_f32_16x16x32_bf16 v[0:3], v[176:179], v[224:227], v[0:3]
	v_mfma_f32_16x16x32_bf16 v[52:55], v[172:175], v[188:191], v[52:55]
	v_mfma_f32_16x16x32_bf16 v[48:51], v[180:183], v[188:191], v[48:51]
	v_mfma_f32_16x16x32_bf16 v[36:39], v[172:175], v[196:199], v[36:39]
	v_mfma_f32_16x16x32_bf16 v[32:35], v[180:183], v[196:199], v[32:35]
	v_mfma_f32_16x16x32_bf16 v[20:23], v[172:175], v[204:207], v[20:23]
	v_mfma_f32_16x16x32_bf16 v[16:19], v[180:183], v[204:207], v[16:19]
	v_mfma_f32_16x16x32_bf16 v[4:7], v[172:175], v[228:231], v[4:7]
	v_mfma_f32_16x16x32_bf16 v[0:3], v[180:183], v[228:231], v[0:3]
	s_setprio 0
	s_barrier
	s_add_i32 s10, s10, 2
	s_add_i32 s8, s8, 0x8000
	s_add_i32 s9, s9, 0x8000

.LBB0_710:
	s_or_b64 exec, exec, s[4:5]
	s_andn2_b64 vcc, exec, s[40:41]
	s_mov_b64 s[4:5], -1
	s_cbranch_vccnz .LBB0_683
	s_mov_b32 s101, 0
	s_andn2_b64 vcc, exec, s[0:1]
	s_cbranch_vccnz .LBB0_682
	s_mov_b32 s101, 1
	s_branch .LBB0_682

.LBB0_792:
	s_cmp_eq_u32 s43, 0
	s_cbranch_scc1 .Lnr_p5
	v_add_u32_e32 v164, 0x10000, v168
	ds_read_b128 v[152:155], v164
	ds_read_b128 v[156:159], v164 offset:1024
	ds_read_b128 v[160:163], v164 offset:2048
	ds_read_b128 v[170:173], v164 offset:3072
	v_add_u32_e32 v164, 0x14000, v168
	ds_read_b128 v[174:177], v164
	ds_read_b128 v[178:181], v164 offset:1024
	ds_read_b128 v[182:185], v164 offset:2048
	ds_read_b128 v[186:189], v164 offset:3072
	ds_read_b128 v[190:193], v169
	ds_read_b128 v[194:197], v169 offset:1024
	ds_read_b128 v[198:201], v169 offset:2048
	ds_read_b128 v[202:205], v169 offset:3072
	ds_read_b128 v[220:223], v169 offset:4096
	ds_read_b128 v[224:227], v169 offset:5120
	ds_read_b128 v[228:231], v169 offset:6144
	ds_read_b128 v[240:243], v169 offset:7168

.Lnb_p5:
	s_add_i32 s53, s37, 0xfff84000
	s_cmp_eq_u32 s52, 28
	s_cselect_b32 s56, s4, s53
	s_cselect_b32 s55, s5, s51
	s_or_b32 s53, s56, 0x4000
	s_mov_b32 m0, s41
	s_nop 0
	buffer_load_dwordx4 v166, s[24:27], s37 offen lds
	s_nop 0
	s_mov_b32 m0, s42
	s_nop 0
	buffer_load_dwordx4 v167, s[24:27], s37 offen lds
	s_waitcnt vmcnt(24)
	s_waitcnt lgkmcnt(0)
	s_barrier
	s_setprio 1
	s_waitcnt lgkmcnt(7)
	v_mfma_f32_16x16x32_bf16 v[148:151], v[152:155], v[190:193], 0
	v_mfma_f32_16x16x32_bf16 v[140:143], v[160:163], v[190:193], 0
	s_waitcnt lgkmcnt(5)
	v_mfma_f32_16x16x32_bf16 v[132:135], v[152:155], v[198:201], 0
	v_mfma_f32_16x16x32_bf16 v[124:127], v[160:163], v[198:201], 0
	s_waitcnt lgkmcnt(3)
	v_mfma_f32_16x16x32_bf16 v[116:119], v[152:155], v[220:223], 0
	v_mfma_f32_16x16x32_bf16 v[108:111], v[160:163], v[220:223], 0
	s_waitcnt lgkmcnt(1)
	v_mfma_f32_16x16x32_bf16 v[76:79], v[152:155], v[228:231], 0
	v_mfma_f32_16x16x32_bf16 v[68:71], v[160:163], v[228:231], 0
	v_mfma_f32_16x16x32_bf16 v[148:151], v[156:159], v[194:197], v[148:151]
	v_mfma_f32_16x16x32_bf16 v[140:143], v[170:173], v[194:197], v[140:143]
	v_mfma_f32_16x16x32_bf16 v[132:135], v[156:159], v[202:205], v[132:135]
	v_mfma_f32_16x16x32_bf16 v[124:127], v[170:173], v[202:205], v[124:127]
	v_mfma_f32_16x16x32_bf16 v[116:119], v[156:159], v[224:227], v[116:119]
	v_mfma_f32_16x16x32_bf16 v[108:111], v[170:173], v[224:227], v[108:111]
	s_waitcnt lgkmcnt(0)
	v_mfma_f32_16x16x32_bf16 v[76:79], v[156:159], v[240:243], v[76:79]
	v_mfma_f32_16x16x32_bf16 v[68:71], v[170:173], v[240:243], v[68:71]
	s_setprio 0
	s_setprio 1
	v_mfma_f32_16x16x32_bf16 v[144:147], v[174:177], v[190:193], 0
	v_mfma_f32_16x16x32_bf16 v[136:139], v[182:185], v[190:193], 0
	v_mfma_f32_16x16x32_bf16 v[128:131], v[174:177], v[198:201], 0
	v_mfma_f32_16x16x32_bf16 v[120:123], v[182:185], v[198:201], 0
	v_mfma_f32_16x16x32_bf16 v[112:115], v[174:177], v[220:223], 0
	v_mfma_f32_16x16x32_bf16 v[104:107], v[182:185], v[220:223], 0
	v_mfma_f32_16x16x32_bf16 v[72:75], v[174:177], v[228:231], 0
	v_mfma_f32_16x16x32_bf16 v[64:67], v[182:185], v[228:231], 0
	v_mfma_f32_16x16x32_bf16 v[144:147], v[178:181], v[194:197], v[144:147]
	v_mfma_f32_16x16x32_bf16 v[136:139], v[186:189], v[194:197], v[136:139]
	v_mfma_f32_16x16x32_bf16 v[128:131], v[178:181], v[202:205], v[128:131]
	v_mfma_f32_16x16x32_bf16 v[120:123], v[186:189], v[202:205], v[120:123]
	v_mfma_f32_16x16x32_bf16 v[112:115], v[178:181], v[224:227], v[112:115]
	v_mfma_f32_16x16x32_bf16 v[104:107], v[186:189], v[224:227], v[104:107]
	v_mfma_f32_16x16x32_bf16 v[72:75], v[178:181], v[240:243], v[72:75]
	v_mfma_f32_16x16x32_bf16 v[64:67], v[186:189], v[240:243], v[64:67]
	s_setprio 0
	s_barrier
	ds_read_b128 v[190:193], v169 offset:16384
	ds_read_b128 v[194:197], v169 offset:17408
	ds_read_b128 v[198:201], v169 offset:18432
	ds_read_b128 v[202:205], v169 offset:19456
	ds_read_b128 v[220:223], v169 offset:20480
	ds_read_b128 v[224:227], v169 offset:21504
	ds_read_b128 v[228:231], v169 offset:22528
	ds_read_b128 v[240:243], v169 offset:23552
	s_mov_b32 m0, s7
	s_nop 0
	buffer_load_dwordx4 v166, s[28:31], s55 offen lds
	s_add_i32 s57, s55, 0x80000
	s_mov_b32 m0, s8
	s_nop 0
	buffer_load_dwordx4 v167, s[28:31], s55 offen lds
	s_nop 0
	s_mov_b32 m0, s9
	s_nop 0
	buffer_load_dwordx4 v166, s[28:31], s57 offen lds
	s_nop 0
	s_mov_b32 m0, s10
	s_nop 0
	buffer_load_dwordx4 v167, s[28:31], s57 offen lds
	s_nop 0
	s_mov_b32 m0, s6
	s_nop 0
	buffer_load_dwordx4 v166, s[24:27], s56 offen lds
	s_nop 0
	s_mov_b32 m0, s11
	s_nop 0
	buffer_load_dwordx4 v167, s[24:27], s56 offen lds
	s_waitcnt vmcnt(24)
	s_waitcnt lgkmcnt(0)
	s_barrier
	s_setprio 1
	s_waitcnt lgkmcnt(7)
	v_mfma_f32_16x16x32_bf16 v[60:63], v[152:155], v[190:193], 0
	v_mfma_f32_16x16x32_bf16 v[52:55], v[160:163], v[190:193], 0
	s_waitcnt lgkmcnt(5)
	v_mfma_f32_16x16x32_bf16 v[44:47], v[152:155], v[198:201], 0
	v_mfma_f32_16x16x32_bf16 v[36:39], v[160:163], v[198:201], 0
	s_waitcnt lgkmcnt(3)
	v_mfma_f32_16x16x32_bf16 v[28:31], v[152:155], v[220:223], 0
	v_mfma_f32_16x16x32_bf16 v[20:23], v[160:163], v[220:223], 0
	s_waitcnt lgkmcnt(1)
	v_mfma_f32_16x16x32_bf16 v[12:15], v[152:155], v[228:231], 0
	v_mfma_f32_16x16x32_bf16 v[4:7], v[160:163], v[228:231], 0
	v_mfma_f32_16x16x32_bf16 v[60:63], v[156:159], v[194:197], v[60:63]
	v_mfma_f32_16x16x32_bf16 v[52:55], v[170:173], v[194:197], v[52:55]
	v_mfma_f32_16x16x32_bf16 v[44:47], v[156:159], v[202:205], v[44:47]
	v_mfma_f32_16x16x32_bf16 v[36:39], v[170:173], v[202:205], v[36:39]
	v_mfma_f32_16x16x32_bf16 v[28:31], v[156:159], v[224:227], v[28:31]
	v_mfma_f32_16x16x32_bf16 v[20:23], v[170:173], v[224:227], v[20:23]
	s_waitcnt lgkmcnt(0)
	v_mfma_f32_16x16x32_bf16 v[12:15], v[156:159], v[240:243], v[12:15]
	v_mfma_f32_16x16x32_bf16 v[4:7], v[170:173], v[240:243], v[4:7]
	s_setprio 0
	s_setprio 1
	v_mfma_f32_16x16x32_bf16 v[56:59], v[174:177], v[190:193], 0
	v_mfma_f32_16x16x32_bf16 v[48:51], v[182:185], v[190:193], 0
	v_mfma_f32_16x16x32_bf16 v[40:43], v[174:177], v[198:201], 0
	v_mfma_f32_16x16x32_bf16 v[32:35], v[182:185], v[198:201], 0
	v_mfma_f32_16x16x32_bf16 v[24:27], v[174:177], v[220:223], 0
	v_mfma_f32_16x16x32_bf16 v[16:19], v[182:185], v[220:223], 0
	v_mfma_f32_16x16x32_bf16 v[8:11], v[174:177], v[228:231], 0
	v_mfma_f32_16x16x32_bf16 v[0:3], v[182:185], v[228:231], 0
	v_mfma_f32_16x16x32_bf16 v[56:59], v[178:181], v[194:197], v[56:59]
	v_mfma_f32_16x16x32_bf16 v[48:51], v[186:189], v[194:197], v[48:51]
	v_mfma_f32_16x16x32_bf16 v[40:43], v[178:181], v[202:205], v[40:43]
	v_mfma_f32_16x16x32_bf16 v[32:35], v[186:189], v[202:205], v[32:35]
	v_mfma_f32_16x16x32_bf16 v[24:27], v[178:181], v[224:227], v[24:27]
	v_mfma_f32_16x16x32_bf16 v[16:19], v[186:189], v[224:227], v[16:19]
	v_mfma_f32_16x16x32_bf16 v[8:11], v[178:181], v[240:243], v[8:11]
	v_mfma_f32_16x16x32_bf16 v[0:3], v[186:189], v[240:243], v[0:3]
	s_setprio 0
	s_barrier
	v_add_u32_e32 v164, 0x18000, v168
	ds_read_b128 v[152:155], v164
	ds_read_b128 v[156:159], v164 offset:1024
	ds_read_b128 v[160:163], v164 offset:2048
	ds_read_b128 v[170:173], v164 offset:3072
	v_add_u32_e32 v164, 0x1c000, v168
	ds_read_b128 v[174:177], v164
	ds_read_b128 v[178:181], v164 offset:1024
	ds_read_b128 v[182:185], v164 offset:2048
	ds_read_b128 v[186:189], v164 offset:3072
	ds_read_b128 v[190:193], v169 offset:32768
	ds_read_b128 v[194:197], v169 offset:33792
	ds_read_b128 v[198:201], v169 offset:34816
	ds_read_b128 v[202:205], v169 offset:35840
	ds_read_b128 v[220:223], v169 offset:36864
	ds_read_b128 v[224:227], v169 offset:37888
	ds_read_b128 v[228:231], v169 offset:38912
	ds_read_b128 v[240:243], v169 offset:39936
	s_add_i32 s56, s56, 0x80000
	s_mov_b32 m0, s12
	s_nop 0
	buffer_load_dwordx4 v166, s[24:27], s56 offen lds
	s_nop 0
	s_mov_b32 m0, s13
	s_nop 0
	buffer_load_dwordx4 v167, s[24:27], s56 offen lds
	s_waitcnt vmcnt(8)
	s_waitcnt lgkmcnt(0)
	s_barrier
	s_setprio 1
	s_waitcnt lgkmcnt(7)
	v_mfma_f32_16x16x32_bf16 v[148:151], v[152:155], v[190:193], v[148:151]
	v_mfma_f32_16x16x32_bf16 v[140:143], v[160:163], v[190:193], v[140:143]
	s_waitcnt lgkmcnt(5)
	v_mfma_f32_16x16x32_bf16 v[132:135], v[152:155], v[198:201], v[132:135]
	v_mfma_f32_16x16x32_bf16 v[124:127], v[160:163], v[198:201], v[124:127]
	s_waitcnt lgkmcnt(3)
	v_mfma_f32_16x16x32_bf16 v[116:119], v[152:155], v[220:223], v[116:119]
	v_mfma_f32_16x16x32_bf16 v[108:111], v[160:163], v[220:223], v[108:111]
	s_waitcnt lgkmcnt(1)
	v_mfma_f32_16x16x32_bf16 v[76:79], v[152:155], v[228:231], v[76:79]
	v_mfma_f32_16x16x32_bf16 v[68:71], v[160:163], v[228:231], v[68:71]
	v_mfma_f32_16x16x32_bf16 v[148:151], v[156:159], v[194:197], v[148:151]
	v_mfma_f32_16x16x32_bf16 v[140:143], v[170:173], v[194:197], v[140:143]
	v_mfma_f32_16x16x32_bf16 v[132:135], v[156:159], v[202:205], v[132:135]
	v_mfma_f32_16x16x32_bf16 v[124:127], v[170:173], v[202:205], v[124:127]
	v_mfma_f32_16x16x32_bf16 v[116:119], v[156:159], v[224:227], v[116:119]
	v_mfma_f32_16x16x32_bf16 v[108:111], v[170:173], v[224:227], v[108:111]
	s_waitcnt lgkmcnt(0)
	v_mfma_f32_16x16x32_bf16 v[76:79], v[156:159], v[240:243], v[76:79]
	v_mfma_f32_16x16x32_bf16 v[68:71], v[170:173], v[240:243], v[68:71]
	s_setprio 0
	s_setprio 1
	v_mfma_f32_16x16x32_bf16 v[144:147], v[174:177], v[190:193], v[144:147]
	v_mfma_f32_16x16x32_bf16 v[136:139], v[182:185], v[190:193], v[136:139]
	v_mfma_f32_16x16x32_bf16 v[128:131], v[174:177], v[198:201], v[128:131]
	v_mfma_f32_16x16x32_bf16 v[120:123], v[182:185], v[198:201], v[120:123]
	v_mfma_f32_16x16x32_bf16 v[112:115], v[174:177], v[220:223], v[112:115]
	v_mfma_f32_16x16x32_bf16 v[104:107], v[182:185], v[220:223], v[104:107]
	v_mfma_f32_16x16x32_bf16 v[72:75], v[174:177], v[228:231], v[72:75]
	v_mfma_f32_16x16x32_bf16 v[64:67], v[182:185], v[228:231], v[64:67]
	v_mfma_f32_16x16x32_bf16 v[144:147], v[178:181], v[194:197], v[144:147]
	v_mfma_f32_16x16x32_bf16 v[136:139], v[186:189], v[194:197], v[136:139]
	v_mfma_f32_16x16x32_bf16 v[128:131], v[178:181], v[202:205], v[128:131]
	v_mfma_f32_16x16x32_bf16 v[120:123], v[186:189], v[202:205], v[120:123]
	v_mfma_f32_16x16x32_bf16 v[112:115], v[178:181], v[224:227], v[112:115]
	v_mfma_f32_16x16x32_bf16 v[104:107], v[186:189], v[224:227], v[104:107]
	v_mfma_f32_16x16x32_bf16 v[72:75], v[178:181], v[240:243], v[72:75]
	v_mfma_f32_16x16x32_bf16 v[64:67], v[186:189], v[240:243], v[64:67]
	s_setprio 0
	s_barrier
	ds_read_b128 v[190:193], v169 offset:49152
	ds_read_b128 v[194:197], v169 offset:50176
	ds_read_b128 v[198:201], v169 offset:51200
	ds_read_b128 v[202:205], v169 offset:52224
	ds_read_b128 v[220:223], v169 offset:53248
	ds_read_b128 v[224:227], v169 offset:54272
	ds_read_b128 v[228:231], v169 offset:55296
	ds_read_b128 v[240:243], v169 offset:56320
	s_or_b32 s56, s55, 0x4000
	s_mov_b32 m0, s16
	s_nop 0
	buffer_load_dwordx4 v166, s[28:31], s56 offen lds
	s_add_i32 s55, s55, 0x84000
	s_mov_b32 m0, s17
	s_nop 0
	buffer_load_dwordx4 v167, s[28:31], s56 offen lds
	s_nop 0
	s_mov_b32 m0, s34
	s_nop 0
	buffer_load_dwordx4 v166, s[28:31], s55 offen lds
	s_nop 0
	s_mov_b32 m0, s40
	s_nop 0
	buffer_load_dwordx4 v167, s[28:31], s55 offen lds
	s_nop 0
	s_mov_b32 m0, s18
	s_nop 0
	buffer_load_dwordx4 v166, s[24:27], s53 offen lds
	s_nop 0
	s_mov_b32 m0, s19
	s_nop 0
	buffer_load_dwordx4 v167, s[24:27], s53 offen lds
	s_waitcnt vmcnt(8)
	s_waitcnt lgkmcnt(0)
	s_barrier
	s_setprio 1
	s_waitcnt lgkmcnt(7)
	v_mfma_f32_16x16x32_bf16 v[60:63], v[152:155], v[190:193], v[60:63]
	v_mfma_f32_16x16x32_bf16 v[52:55], v[160:163], v[190:193], v[52:55]
	s_waitcnt lgkmcnt(5)
	v_mfma_f32_16x16x32_bf16 v[44:47], v[152:155], v[198:201], v[44:47]
	v_mfma_f32_16x16x32_bf16 v[36:39], v[160:163], v[198:201], v[36:39]
	s_waitcnt lgkmcnt(3)
	v_mfma_f32_16x16x32_bf16 v[28:31], v[152:155], v[220:223], v[28:31]
	v_mfma_f32_16x16x32_bf16 v[20:23], v[160:163], v[220:223], v[20:23]
	s_waitcnt lgkmcnt(1)
	v_mfma_f32_16x16x32_bf16 v[12:15], v[152:155], v[228:231], v[12:15]
	v_mfma_f32_16x16x32_bf16 v[4:7], v[160:163], v[228:231], v[4:7]
	v_mfma_f32_16x16x32_bf16 v[60:63], v[156:159], v[194:197], v[60:63]
	v_mfma_f32_16x16x32_bf16 v[52:55], v[170:173], v[194:197], v[52:55]
	v_mfma_f32_16x16x32_bf16 v[44:47], v[156:159], v[202:205], v[44:47]
	v_mfma_f32_16x16x32_bf16 v[36:39], v[170:173], v[202:205], v[36:39]
	v_mfma_f32_16x16x32_bf16 v[28:31], v[156:159], v[224:227], v[28:31]
	v_mfma_f32_16x16x32_bf16 v[20:23], v[170:173], v[224:227], v[20:23]
	s_waitcnt lgkmcnt(0)
	v_mfma_f32_16x16x32_bf16 v[12:15], v[156:159], v[240:243], v[12:15]
	v_mfma_f32_16x16x32_bf16 v[4:7], v[170:173], v[240:243], v[4:7]
	s_setprio 0
	s_setprio 1
	v_mfma_f32_16x16x32_bf16 v[56:59], v[174:177], v[190:193], v[56:59]
	v_mfma_f32_16x16x32_bf16 v[48:51], v[182:185], v[190:193], v[48:51]
	v_mfma_f32_16x16x32_bf16 v[40:43], v[174:177], v[198:201], v[40:43]
	v_mfma_f32_16x16x32_bf16 v[32:35], v[182:185], v[198:201], v[32:35]
	v_mfma_f32_16x16x32_bf16 v[24:27], v[174:177], v[220:223], v[24:27]
	v_mfma_f32_16x16x32_bf16 v[16:19], v[182:185], v[220:223], v[16:19]
	v_mfma_f32_16x16x32_bf16 v[8:11], v[174:177], v[228:231], v[8:11]
	v_mfma_f32_16x16x32_bf16 v[0:3], v[182:185], v[228:231], v[0:3]
	v_mfma_f32_16x16x32_bf16 v[56:59], v[178:181], v[194:197], v[56:59]
	v_mfma_f32_16x16x32_bf16 v[48:51], v[186:189], v[194:197], v[48:51]
	v_mfma_f32_16x16x32_bf16 v[40:43], v[178:181], v[202:205], v[40:43]
	v_mfma_f32_16x16x32_bf16 v[32:35], v[186:189], v[202:205], v[32:35]
	v_mfma_f32_16x16x32_bf16 v[24:27], v[178:181], v[224:227], v[24:27]
	v_mfma_f32_16x16x32_bf16 v[16:19], v[186:189], v[224:227], v[16:19]
	v_mfma_f32_16x16x32_bf16 v[8:11], v[178:181], v[240:243], v[8:11]
	v_mfma_f32_16x16x32_bf16 v[0:3], v[186:189], v[240:243], v[0:3]
	s_setprio 0
	s_barrier
	s_add_i32 s52, s52, 2
	s_add_i32 s37, s37, 0x8000
	s_add_i32 s51, s51, 0x8000

.LBB0_798:
	s_lshl_b32 s51, s36, 15
	s_lshl_b32 s4, s33, 11
	s_add_u32 s4, s14, s4
	s_addc_u32 s5, s15, 0
	s_mov_b64 s[36:37], s[4:5]
	v_pk_mul_f32 v[146:147], v[150:151], v[146:147]
	v_lshl_add_u64 v[152:153], s[36:37], 0, v[80:81]
	global_load_dwordx2 v[170:171], v[152:153], off
	s_add_u32 s36, s4, 0x80
	s_addc_u32 s37, s5, 0
	v_pk_mul_f32 v[144:145], v[148:149], v[144:145]
	v_lshl_add_u64 v[152:153], s[36:37], 0, v[80:81]
	global_load_dwordx2 v[164:165], v[152:153], off
	s_add_u32 s36, s4, 0x100
	s_addc_u32 s37, s5, 0
	s_mul_i32 s33, s33, 0x2c0000
	v_lshl_add_u64 v[152:153], s[36:37], 0, v[80:81]
	global_load_dwordx2 v[162:163], v[152:153], off
	s_add_u32 s36, s4, 0x180
	s_addc_u32 s37, s5, 0
	v_pk_mul_f32 v[138:139], v[142:143], v[138:139]
	v_lshl_add_u64 v[152:153], s[36:37], 0, v[80:81]
	global_load_dwordx2 v[160:161], v[152:153], off
	s_add_u32 s36, s4, 0x400
	s_addc_u32 s37, s5, 0
	v_pk_mul_f32 v[136:137], v[140:141], v[136:137]
	v_lshl_add_u64 v[152:153], s[36:37], 0, v[80:81]
	s_add_u32 s36, s4, 0x480
	s_addc_u32 s37, s5, 0
	global_load_dwordx2 v[158:159], v[152:153], off
	v_pk_mul_f32 v[130:131], v[134:135], v[130:131]
	v_lshl_add_u64 v[152:153], s[36:37], 0, v[80:81]
	s_add_u32 s36, s4, 0x500
	s_addc_u32 s37, s5, 0
	s_add_u32 s4, s4, 0x580
	global_load_dwordx2 v[156:157], v[152:153], off
	s_addc_u32 s5, s5, 0
	v_lshl_add_u64 v[152:153], s[36:37], 0, v[80:81]
	global_load_dwordx2 v[154:155], v[152:153], off
	s_add_i32 s33, s33, s51
	v_lshl_add_u64 v[152:153], s[4:5], 0, v[80:81]
	global_load_dwordx2 v[152:153], v[152:153], off
	s_add_u32 s4, s20, s33
	s_addc_u32 s5, s68, 0
	s_mov_b64 s[36:37], s[4:5]
	v_pk_mul_f32 v[128:129], v[132:133], v[128:129]
	v_pk_mul_f32 v[122:123], v[126:127], v[122:123]
	v_pk_mul_f32 v[120:121], v[124:125], v[120:121]
	s_add_u32 s4, s4, 0x800
	s_addc_u32 s5, s5, 0
	v_pk_mul_f32 v[114:115], v[118:119], v[114:115]
	v_pk_mul_f32 v[112:113], v[116:117], v[112:113]
	v_pk_mul_f32 v[106:107], v[110:111], v[106:107]
	v_pk_mul_f32 v[104:105], v[108:109], v[104:105]
	v_pk_mul_f32 v[74:75], v[78:79], v[74:75]
	v_pk_mul_f32 v[72:73], v[76:77], v[72:73]
	v_pk_mul_f32 v[66:67], v[70:71], v[66:67]
	v_pk_mul_f32 v[64:65], v[68:69], v[64:65]
	v_pk_mul_f32 v[58:59], v[62:63], v[58:59]
	v_pk_mul_f32 v[56:57], v[60:61], v[56:57]
	v_pk_mul_f32 v[50:51], v[54:55], v[50:51]
	v_pk_mul_f32 v[48:49], v[52:53], v[48:49]
	v_pk_mul_f32 v[42:43], v[46:47], v[42:43]
	v_pk_mul_f32 v[40:41], v[44:45], v[40:41]
	v_pk_mul_f32 v[34:35], v[38:39], v[34:35]
	v_pk_mul_f32 v[32:33], v[36:37], v[32:33]
	v_pk_mul_f32 v[26:27], v[30:31], v[26:27]
	v_pk_mul_f32 v[24:25], v[28:29], v[24:25]
	v_pk_mul_f32 v[18:19], v[22:23], v[18:19]
	v_pk_mul_f32 v[16:17], v[20:21], v[16:17]
	v_pk_mul_f32 v[10:11], v[14:15], v[10:11]
	v_pk_mul_f32 v[8:9], v[12:13], v[8:9]
	v_pk_mul_f32 v[2:3], v[6:7], v[2:3]
	v_pk_mul_f32 v[0:1], v[4:5], v[0:1]
	s_waitcnt vmcnt(7)
	v_cvt_f32_u32_e32 v171, v171
	v_cvt_f32_u32_e32 v170, v170
	v_fmac_f32_e32 v170, 0x4f800000, v171
	v_fmamk_f32 v170, v170, 0x30000000, v234
	v_rsq_f32_e32 v178, v170
	s_nop 0
	v_mul_f32_e32 v174, 0xbfb8aa3b, v178
	v_pk_mul_f32 v[172:173], v[150:151], v[174:175] op_sel_hi:[1,0]
	v_pk_mul_f32 v[170:171], v[148:149], v[174:175] op_sel_hi:[1,0]
	v_pk_mul_f32 v[176:177], v[142:143], v[174:175] op_sel_hi:[1,0]
	v_pk_mul_f32 v[174:175], v[140:141], v[174:175] op_sel_hi:[1,0]
	v_mul_f32_e32 v178, v178, v178
	v_pk_mul_f32 v[180:181], v[146:147], v[178:179] op_sel_hi:[1,0]
	v_exp_f32_e32 v170, v170
	v_exp_f32_e32 v174, v174
	v_exp_f32_e32 v171, v171
	v_exp_f32_e32 v175, v175
	v_exp_f32_e32 v172, v172
	v_exp_f32_e32 v176, v176
	v_exp_f32_e32 v173, v173
	v_exp_f32_e32 v177, v177
	v_pk_mul_f32 v[182:183], v[144:145], v[178:179] op_sel_hi:[1,0]
	v_pk_add_f32 v[144:145], v[170:171], 1.0 op_sel_hi:[1,0]
	v_pk_add_f32 v[146:147], v[172:173], 1.0 op_sel_hi:[1,0]
	v_pk_add_f32 v[150:151], v[176:177], 1.0 op_sel_hi:[1,0]
	v_pk_add_f32 v[148:149], v[174:175], 1.0 op_sel_hi:[1,0]
	v_pk_mul_f32 v[138:139], v[138:139], v[178:179] op_sel_hi:[1,0]
	v_pk_mul_f32 v[136:137], v[136:137], v[178:179] op_sel_hi:[1,0]
	v_rcp_f32_e32 v144, v144
	v_rcp_f32_e32 v148, v148
	v_rcp_f32_e32 v145, v145
	v_rcp_f32_e32 v149, v149
	v_rcp_f32_e32 v146, v146
	v_rcp_f32_e32 v150, v150
	v_rcp_f32_e32 v147, v147
	v_rcp_f32_e32 v151, v151
	s_nop 0
	v_pk_mul_f32 v[140:141], v[180:181], v[146:147]
	v_pk_mul_f32 v[142:143], v[182:183], v[144:145]
	v_pk_mul_f32 v[144:145], v[138:139], v[150:151]
	v_pk_mul_f32 v[138:139], v[136:137], v[148:149]
	v_cvt_pk_bf16_f32 v136, v142, v143
	v_cvt_pk_bf16_f32 v137, v140, v141
	v_cvt_pk_bf16_f32 v138, v138, v139
	v_cvt_pk_bf16_f32 v139, v144, v145
	v_lshl_add_u64 v[140:141], s[36:37], 0, v[82:83]
	global_store_dwordx4 v[140:141], v[136:139], off nt
	s_waitcnt vmcnt(7)
	s_nop 0
	v_cvt_f32_u32_e32 v136, v165
	v_cvt_f32_u32_e32 v137, v164
	v_fmac_f32_e32 v137, 0x4f800000, v136
	v_fmamk_f32 v136, v137, 0x30000000, v234
	v_rsq_f32_e32 v144, v136
	s_nop 0
	v_mul_f32_e32 v140, 0xbfb8aa3b, v144
	v_pk_mul_f32 v[138:139], v[134:135], v[140:141] op_sel_hi:[1,0]
	v_pk_mul_f32 v[136:137], v[132:133], v[140:141] op_sel_hi:[1,0]
	v_pk_mul_f32 v[142:143], v[126:127], v[140:141] op_sel_hi:[1,0]
	v_pk_mul_f32 v[140:141], v[124:125], v[140:141] op_sel_hi:[1,0]
	v_mul_f32_e32 v144, v144, v144
	v_pk_mul_f32 v[146:147], v[130:131], v[144:145] op_sel_hi:[1,0]
	v_exp_f32_e32 v136, v136
	v_exp_f32_e32 v140, v140
	v_exp_f32_e32 v137, v137
	v_exp_f32_e32 v141, v141
	v_exp_f32_e32 v138, v138
	v_exp_f32_e32 v142, v142
	v_exp_f32_e32 v139, v139
	v_exp_f32_e32 v143, v143
	v_pk_mul_f32 v[148:149], v[128:129], v[144:145] op_sel_hi:[1,0]
	v_pk_add_f32 v[128:129], v[136:137], 1.0 op_sel_hi:[1,0]
	v_pk_add_f32 v[130:131], v[138:139], 1.0 op_sel_hi:[1,0]
	v_pk_add_f32 v[134:135], v[142:143], 1.0 op_sel_hi:[1,0]
	v_pk_add_f32 v[132:133], v[140:141], 1.0 op_sel_hi:[1,0]
	v_pk_mul_f32 v[122:123], v[122:123], v[144:145] op_sel_hi:[1,0]
	v_pk_mul_f32 v[120:121], v[120:121], v[144:145] op_sel_hi:[1,0]
	v_rcp_f32_e32 v128, v128
	v_rcp_f32_e32 v132, v132
	v_rcp_f32_e32 v129, v129
	v_rcp_f32_e32 v133, v133
	v_rcp_f32_e32 v130, v130
	v_rcp_f32_e32 v134, v134
	v_rcp_f32_e32 v131, v131
	v_rcp_f32_e32 v135, v135
	s_nop 0
	v_pk_mul_f32 v[124:125], v[146:147], v[130:131]
	v_pk_mul_f32 v[126:127], v[148:149], v[128:129]
	v_pk_mul_f32 v[128:129], v[122:123], v[134:135]
	v_pk_mul_f32 v[122:123], v[120:121], v[132:133]
	v_cvt_pk_bf16_f32 v120, v126, v127
	v_cvt_pk_bf16_f32 v121, v124, v125
	v_cvt_pk_bf16_f32 v122, v122, v123
	v_cvt_pk_bf16_f32 v123, v128, v129
	v_lshl_add_u64 v[124:125], s[4:5], 0, v[82:83]
	global_store_dwordx4 v[124:125], v[120:123], off nt
	s_or_b32 s4, s33, 0x1000
	s_add_u32 s4, s20, s4
	s_waitcnt vmcnt(7)
	v_cvt_f32_u32_e32 v120, v163
	v_cvt_f32_u32_e32 v121, v162
	s_addc_u32 s5, s68, 0
	v_fmac_f32_e32 v121, 0x4f800000, v120
	v_fmamk_f32 v120, v121, 0x30000000, v234
	v_rsq_f32_e32 v128, v120
	s_nop 0
	v_mul_f32_e32 v124, 0xbfb8aa3b, v128
	v_pk_mul_f32 v[122:123], v[118:119], v[124:125] op_sel_hi:[1,0]
	v_pk_mul_f32 v[120:121], v[116:117], v[124:125] op_sel_hi:[1,0]
	v_pk_mul_f32 v[126:127], v[110:111], v[124:125] op_sel_hi:[1,0]
	v_pk_mul_f32 v[124:125], v[108:109], v[124:125] op_sel_hi:[1,0]
	v_mul_f32_e32 v128, v128, v128
	v_pk_mul_f32 v[130:131], v[114:115], v[128:129] op_sel_hi:[1,0]
	v_exp_f32_e32 v120, v120
	v_exp_f32_e32 v124, v124
	v_exp_f32_e32 v121, v121
	v_exp_f32_e32 v125, v125
	v_exp_f32_e32 v122, v122
	v_exp_f32_e32 v126, v126
	v_exp_f32_e32 v123, v123
	v_exp_f32_e32 v127, v127
	v_pk_mul_f32 v[132:133], v[112:113], v[128:129] op_sel_hi:[1,0]
	v_pk_add_f32 v[112:113], v[120:121], 1.0 op_sel_hi:[1,0]
	v_pk_add_f32 v[114:115], v[122:123], 1.0 op_sel_hi:[1,0]
	v_pk_add_f32 v[118:119], v[126:127], 1.0 op_sel_hi:[1,0]
	v_pk_add_f32 v[116:117], v[124:125], 1.0 op_sel_hi:[1,0]
	v_pk_mul_f32 v[106:107], v[106:107], v[128:129] op_sel_hi:[1,0]
	v_pk_mul_f32 v[104:105], v[104:105], v[128:129] op_sel_hi:[1,0]
	v_rcp_f32_e32 v112, v112
	v_rcp_f32_e32 v116, v116
	v_rcp_f32_e32 v113, v113
	v_rcp_f32_e32 v117, v117
	v_rcp_f32_e32 v114, v114
	v_rcp_f32_e32 v118, v118
	v_rcp_f32_e32 v115, v115
	v_rcp_f32_e32 v119, v119
	s_nop 0
	v_pk_mul_f32 v[108:109], v[130:131], v[114:115]
	v_pk_mul_f32 v[110:111], v[132:133], v[112:113]
	v_pk_mul_f32 v[112:113], v[106:107], v[118:119]
	v_pk_mul_f32 v[106:107], v[104:105], v[116:117]
	v_cvt_pk_bf16_f32 v104, v110, v111
	v_cvt_pk_bf16_f32 v105, v108, v109
	v_cvt_pk_bf16_f32 v106, v106, v107
	v_cvt_pk_bf16_f32 v107, v112, v113
	v_lshl_add_u64 v[108:109], s[4:5], 0, v[82:83]
	global_store_dwordx4 v[108:109], v[104:107], off nt
	s_or_b32 s4, s33, 0x1800
	s_add_u32 s4, s20, s4
	s_waitcnt vmcnt(7)
	v_cvt_f32_u32_e32 v104, v161
	v_cvt_f32_u32_e32 v105, v160
	s_addc_u32 s5, s68, 0
	v_fmac_f32_e32 v105, 0x4f800000, v104
	v_fmamk_f32 v104, v105, 0x30000000, v234
	v_rsq_f32_e32 v112, v104
	s_nop 0
	v_mul_f32_e32 v108, 0xbfb8aa3b, v112
	v_pk_mul_f32 v[106:107], v[78:79], v[108:109] op_sel_hi:[1,0]
	v_pk_mul_f32 v[104:105], v[76:77], v[108:109] op_sel_hi:[1,0]
	v_pk_mul_f32 v[110:111], v[70:71], v[108:109] op_sel_hi:[1,0]
	v_pk_mul_f32 v[108:109], v[68:69], v[108:109] op_sel_hi:[1,0]
	v_mul_f32_e32 v112, v112, v112
	v_pk_mul_f32 v[114:115], v[74:75], v[112:113] op_sel_hi:[1,0]
	v_exp_f32_e32 v104, v104
	v_exp_f32_e32 v108, v108
	v_exp_f32_e32 v105, v105
	v_exp_f32_e32 v109, v109
	v_exp_f32_e32 v106, v106
	v_exp_f32_e32 v110, v110
	v_exp_f32_e32 v107, v107
	v_exp_f32_e32 v111, v111
	v_pk_mul_f32 v[116:117], v[72:73], v[112:113] op_sel_hi:[1,0]
	v_pk_add_f32 v[72:73], v[104:105], 1.0 op_sel_hi:[1,0]
	v_pk_add_f32 v[74:75], v[106:107], 1.0 op_sel_hi:[1,0]
	v_pk_add_f32 v[78:79], v[110:111], 1.0 op_sel_hi:[1,0]
	v_pk_add_f32 v[76:77], v[108:109], 1.0 op_sel_hi:[1,0]
	v_pk_mul_f32 v[66:67], v[66:67], v[112:113] op_sel_hi:[1,0]
	v_pk_mul_f32 v[64:65], v[64:65], v[112:113] op_sel_hi:[1,0]
	v_rcp_f32_e32 v72, v72
	v_rcp_f32_e32 v76, v76
	v_rcp_f32_e32 v73, v73
	v_rcp_f32_e32 v77, v77
	v_rcp_f32_e32 v74, v74
	v_rcp_f32_e32 v78, v78
	v_rcp_f32_e32 v75, v75
	v_rcp_f32_e32 v79, v79
	s_nop 0
	v_pk_mul_f32 v[68:69], v[114:115], v[74:75]
	v_pk_mul_f32 v[70:71], v[116:117], v[72:73]
	v_pk_mul_f32 v[72:73], v[66:67], v[78:79]
	v_pk_mul_f32 v[66:67], v[64:65], v[76:77]
	v_cvt_pk_bf16_f32 v64, v70, v71
	v_cvt_pk_bf16_f32 v65, v68, v69
	v_cvt_pk_bf16_f32 v66, v66, v67
	v_cvt_pk_bf16_f32 v67, v72, v73
	v_lshl_add_u64 v[68:69], s[4:5], 0, v[82:83]
	global_store_dwordx4 v[68:69], v[64:67], off nt
	s_add_i32 s4, s33, 0x160000
	s_add_u32 s4, s20, s4
	s_waitcnt vmcnt(7)
	v_cvt_f32_u32_e32 v64, v159
	v_cvt_f32_u32_e32 v65, v158
	s_addc_u32 s5, s68, 0
	v_fmac_f32_e32 v65, 0x4f800000, v64
	v_fmamk_f32 v64, v65, 0x30000000, v234
	v_rsq_f32_e32 v72, v64
	s_nop 0
	v_mul_f32_e32 v68, 0xbfb8aa3b, v72
	v_pk_mul_f32 v[66:67], v[62:63], v[68:69] op_sel_hi:[1,0]
	v_pk_mul_f32 v[64:65], v[60:61], v[68:69] op_sel_hi:[1,0]
	v_pk_mul_f32 v[70:71], v[54:55], v[68:69] op_sel_hi:[1,0]
	v_pk_mul_f32 v[68:69], v[52:53], v[68:69] op_sel_hi:[1,0]
	v_mul_f32_e32 v72, v72, v72
	v_pk_mul_f32 v[74:75], v[58:59], v[72:73] op_sel_hi:[1,0]
	v_exp_f32_e32 v64, v64
	v_exp_f32_e32 v68, v68
	v_exp_f32_e32 v65, v65
	v_exp_f32_e32 v69, v69
	v_exp_f32_e32 v66, v66
	v_exp_f32_e32 v70, v70
	v_exp_f32_e32 v67, v67
	v_exp_f32_e32 v71, v71
	v_pk_mul_f32 v[76:77], v[56:57], v[72:73] op_sel_hi:[1,0]
	v_pk_add_f32 v[56:57], v[64:65], 1.0 op_sel_hi:[1,0]
	v_pk_add_f32 v[58:59], v[66:67], 1.0 op_sel_hi:[1,0]
	v_pk_add_f32 v[62:63], v[70:71], 1.0 op_sel_hi:[1,0]
	v_pk_add_f32 v[60:61], v[68:69], 1.0 op_sel_hi:[1,0]
	v_pk_mul_f32 v[50:51], v[50:51], v[72:73] op_sel_hi:[1,0]
	v_pk_mul_f32 v[48:49], v[48:49], v[72:73] op_sel_hi:[1,0]
	v_rcp_f32_e32 v56, v56
	v_rcp_f32_e32 v60, v60
	v_rcp_f32_e32 v57, v57
	v_rcp_f32_e32 v61, v61
	v_rcp_f32_e32 v58, v58
	v_rcp_f32_e32 v62, v62
	v_rcp_f32_e32 v59, v59
	v_rcp_f32_e32 v63, v63
	s_nop 0
	v_pk_mul_f32 v[52:53], v[74:75], v[58:59]
	v_pk_mul_f32 v[54:55], v[76:77], v[56:57]
	v_pk_mul_f32 v[56:57], v[50:51], v[62:63]
	v_pk_mul_f32 v[50:51], v[48:49], v[60:61]
	v_cvt_pk_bf16_f32 v48, v54, v55
	v_cvt_pk_bf16_f32 v49, v52, v53
	v_cvt_pk_bf16_f32 v50, v50, v51
	v_cvt_pk_bf16_f32 v51, v56, v57
	v_lshl_add_u64 v[52:53], s[4:5], 0, v[82:83]
	global_store_dwordx4 v[52:53], v[48:51], off nt
	s_add_i32 s4, s33, 0x160800
	s_add_u32 s4, s20, s4
	s_waitcnt vmcnt(7)
	v_cvt_f32_u32_e32 v48, v157
	v_cvt_f32_u32_e32 v49, v156
	s_addc_u32 s5, s68, 0
	v_fmac_f32_e32 v49, 0x4f800000, v48
	v_fmamk_f32 v48, v49, 0x30000000, v234
	v_rsq_f32_e32 v56, v48
	s_nop 0
	v_mul_f32_e32 v52, 0xbfb8aa3b, v56
	v_pk_mul_f32 v[50:51], v[46:47], v[52:53] op_sel_hi:[1,0]
	v_pk_mul_f32 v[48:49], v[44:45], v[52:53] op_sel_hi:[1,0]
	v_pk_mul_f32 v[54:55], v[38:39], v[52:53] op_sel_hi:[1,0]
	v_pk_mul_f32 v[52:53], v[36:37], v[52:53] op_sel_hi:[1,0]
	v_mul_f32_e32 v56, v56, v56
	v_pk_mul_f32 v[58:59], v[42:43], v[56:57] op_sel_hi:[1,0]
	v_exp_f32_e32 v48, v48
	v_exp_f32_e32 v52, v52
	v_exp_f32_e32 v49, v49
	v_exp_f32_e32 v53, v53
	v_exp_f32_e32 v50, v50
	v_exp_f32_e32 v54, v54
	v_exp_f32_e32 v51, v51
	v_exp_f32_e32 v55, v55
	v_pk_mul_f32 v[60:61], v[40:41], v[56:57] op_sel_hi:[1,0]
	v_pk_add_f32 v[40:41], v[48:49], 1.0 op_sel_hi:[1,0]
	v_pk_add_f32 v[42:43], v[50:51], 1.0 op_sel_hi:[1,0]
	v_pk_add_f32 v[46:47], v[54:55], 1.0 op_sel_hi:[1,0]
	v_pk_add_f32 v[44:45], v[52:53], 1.0 op_sel_hi:[1,0]
	v_pk_mul_f32 v[34:35], v[34:35], v[56:57] op_sel_hi:[1,0]
	v_pk_mul_f32 v[32:33], v[32:33], v[56:57] op_sel_hi:[1,0]
	v_rcp_f32_e32 v40, v40
	v_rcp_f32_e32 v44, v44
	v_rcp_f32_e32 v41, v41
	v_rcp_f32_e32 v45, v45
	v_rcp_f32_e32 v42, v42
	v_rcp_f32_e32 v46, v46
	v_rcp_f32_e32 v43, v43
	v_rcp_f32_e32 v47, v47
	s_nop 0
	v_pk_mul_f32 v[36:37], v[58:59], v[42:43]
	v_pk_mul_f32 v[38:39], v[60:61], v[40:41]
	v_pk_mul_f32 v[40:41], v[34:35], v[46:47]
	v_pk_mul_f32 v[34:35], v[32:33], v[44:45]
	v_cvt_pk_bf16_f32 v32, v38, v39
	v_cvt_pk_bf16_f32 v33, v36, v37
	v_cvt_pk_bf16_f32 v34, v34, v35
	v_cvt_pk_bf16_f32 v35, v40, v41
	v_lshl_add_u64 v[36:37], s[4:5], 0, v[82:83]
	global_store_dwordx4 v[36:37], v[32:35], off nt
	s_add_i32 s4, s33, 0x161000
	s_add_u32 s4, s20, s4
	s_waitcnt vmcnt(7)
	v_cvt_f32_u32_e32 v32, v155
	v_cvt_f32_u32_e32 v33, v154
	s_addc_u32 s5, s68, 0
	s_add_i32 s33, s33, 0x161800
	v_fmac_f32_e32 v33, 0x4f800000, v32
	v_fmamk_f32 v32, v33, 0x30000000, v234
	v_rsq_f32_e32 v40, v32
	s_nop 0
	v_mul_f32_e32 v36, 0xbfb8aa3b, v40
	v_pk_mul_f32 v[34:35], v[30:31], v[36:37] op_sel_hi:[1,0]
	v_pk_mul_f32 v[32:33], v[28:29], v[36:37] op_sel_hi:[1,0]
	v_pk_mul_f32 v[38:39], v[22:23], v[36:37] op_sel_hi:[1,0]
	v_pk_mul_f32 v[36:37], v[20:21], v[36:37] op_sel_hi:[1,0]
	v_mul_f32_e32 v40, v40, v40
	v_pk_mul_f32 v[42:43], v[26:27], v[40:41] op_sel_hi:[1,0]
	v_exp_f32_e32 v32, v32
	v_exp_f32_e32 v36, v36
	v_exp_f32_e32 v33, v33
	v_exp_f32_e32 v37, v37
	v_exp_f32_e32 v34, v34
	v_exp_f32_e32 v38, v38
	v_exp_f32_e32 v35, v35
	v_exp_f32_e32 v39, v39
	v_pk_mul_f32 v[44:45], v[24:25], v[40:41] op_sel_hi:[1,0]
	v_pk_add_f32 v[24:25], v[32:33], 1.0 op_sel_hi:[1,0]
	v_pk_add_f32 v[26:27], v[34:35], 1.0 op_sel_hi:[1,0]
	v_pk_add_f32 v[30:31], v[38:39], 1.0 op_sel_hi:[1,0]
	v_pk_add_f32 v[28:29], v[36:37], 1.0 op_sel_hi:[1,0]
	v_pk_mul_f32 v[18:19], v[18:19], v[40:41] op_sel_hi:[1,0]
	v_pk_mul_f32 v[16:17], v[16:17], v[40:41] op_sel_hi:[1,0]
	v_rcp_f32_e32 v24, v24
	v_rcp_f32_e32 v28, v28
	v_rcp_f32_e32 v25, v25
	v_rcp_f32_e32 v29, v29
	v_rcp_f32_e32 v26, v26
	v_rcp_f32_e32 v30, v30
	v_rcp_f32_e32 v27, v27
	v_rcp_f32_e32 v31, v31
	s_nop 0
	v_pk_mul_f32 v[20:21], v[42:43], v[26:27]
	v_pk_mul_f32 v[22:23], v[44:45], v[24:25]
	v_pk_mul_f32 v[24:25], v[18:19], v[30:31]
	v_pk_mul_f32 v[18:19], v[16:17], v[28:29]
	v_cvt_pk_bf16_f32 v16, v22, v23
	v_cvt_pk_bf16_f32 v17, v20, v21
	v_cvt_pk_bf16_f32 v18, v18, v19
	v_cvt_pk_bf16_f32 v19, v24, v25
	v_lshl_add_u64 v[20:21], s[4:5], 0, v[82:83]
	global_store_dwordx4 v[20:21], v[16:19], off nt
	s_add_u32 s4, s20, s33
	s_addc_u32 s5, s68, 0
	s_waitcnt vmcnt(7)
	v_cvt_f32_u32_e32 v16, v153
	v_cvt_f32_u32_e32 v17, v152
	s_andn2_b64 vcc, exec, s[38:39]
	v_fmac_f32_e32 v17, 0x4f800000, v16
	v_fmamk_f32 v16, v17, 0x30000000, v234
	v_rsq_f32_e32 v24, v16
	s_nop 0
	v_mul_f32_e32 v20, 0xbfb8aa3b, v24
	v_pk_mul_f32 v[18:19], v[14:15], v[20:21] op_sel_hi:[1,0]
	v_pk_mul_f32 v[16:17], v[12:13], v[20:21] op_sel_hi:[1,0]
	v_pk_mul_f32 v[22:23], v[6:7], v[20:21] op_sel_hi:[1,0]
	v_pk_mul_f32 v[20:21], v[4:5], v[20:21] op_sel_hi:[1,0]
	v_mul_f32_e32 v24, v24, v24
	v_pk_mul_f32 v[26:27], v[10:11], v[24:25] op_sel_hi:[1,0]
	v_exp_f32_e32 v16, v16
	v_exp_f32_e32 v20, v20
	v_exp_f32_e32 v17, v17
	v_exp_f32_e32 v21, v21
	v_exp_f32_e32 v18, v18
	v_exp_f32_e32 v22, v22
	v_exp_f32_e32 v19, v19
	v_exp_f32_e32 v23, v23
	v_pk_mul_f32 v[28:29], v[8:9], v[24:25] op_sel_hi:[1,0]
	v_pk_add_f32 v[8:9], v[16:17], 1.0 op_sel_hi:[1,0]
	v_pk_add_f32 v[10:11], v[18:19], 1.0 op_sel_hi:[1,0]
	v_pk_add_f32 v[14:15], v[22:23], 1.0 op_sel_hi:[1,0]
	v_pk_add_f32 v[12:13], v[20:21], 1.0 op_sel_hi:[1,0]
	v_pk_mul_f32 v[2:3], v[2:3], v[24:25] op_sel_hi:[1,0]
	v_pk_mul_f32 v[0:1], v[0:1], v[24:25] op_sel_hi:[1,0]
	v_rcp_f32_e32 v8, v8
	v_rcp_f32_e32 v12, v12
	v_rcp_f32_e32 v9, v9
	v_rcp_f32_e32 v13, v13
	v_rcp_f32_e32 v10, v10
	v_rcp_f32_e32 v14, v14
	v_rcp_f32_e32 v11, v11
	v_rcp_f32_e32 v15, v15
	s_nop 0
	v_pk_mul_f32 v[4:5], v[26:27], v[10:11]
	v_pk_mul_f32 v[6:7], v[28:29], v[8:9]
	v_pk_mul_f32 v[8:9], v[2:3], v[14:15]
	v_pk_mul_f32 v[2:3], v[0:1], v[12:13]
	v_cvt_pk_bf16_f32 v0, v6, v7
	v_cvt_pk_bf16_f32 v1, v4, v5
	v_cvt_pk_bf16_f32 v2, v2, v3
	v_cvt_pk_bf16_f32 v3, v8, v9
	v_lshl_add_u64 v[4:5], s[4:5], 0, v[82:83]
	s_mov_b64 s[4:5], -1
	global_store_dwordx4 v[4:5], v[0:3], off nt
	s_cbranch_vccnz .LBB0_791
	s_mov_b32 s101, 0
	s_andn2_b64 vcc, exec, s[0:1]
	s_cbranch_vccnz .LBB0_790
	s_mov_b32 s101, 1
	s_branch .LBB0_790

.LBB0_878:
	s_cmp_eq_u32 s88, 0
	s_cbranch_scc1 .Lnr_p6
	v_add_u32_e32 v156, 0x10000, v222
	v_add_u32_e32 v180, 0x14000, v222
	ds_read_b128 v[128:131], v156
	ds_read_b128 v[140:143], v156 offset:1024
	ds_read_b128 v[152:155], v156 offset:2048
	ds_read_b128 v[156:159], v156 offset:3072
	ds_read_b128 v[168:171], v180
	ds_read_b128 v[172:175], v180 offset:1024
	ds_read_b128 v[176:179], v180 offset:2048
	ds_read_b128 v[180:183], v180 offset:3072
	ds_read_b128 v[184:187], v223
	ds_read_b128 v[188:191], v223 offset:1024
	ds_read_b128 v[192:195], v223 offset:2048
	ds_read_b128 v[196:199], v223 offset:3072
	ds_read_b128 v[200:203], v223 offset:4096
	ds_read_b128 v[204:207], v223 offset:5120
	ds_read_b128 v[224:227], v223 offset:6144
	ds_read_b128 v[228:231], v223 offset:7168

.Lnb_p6:
	s_add_i32 s11, s8, 0xffea4000
	s_cmpk_eq_i32 s10, 0x54
	s_cselect_b32 s13, s6, s11
	s_cselect_b32 s12, s7, s9
	s_or_b32 s11, s13, 0x4000
	s_mov_b32 m0, s87
	s_nop 0
	buffer_load_dwordx4 v220, s[20:23], s8 offen lds
	s_nop 0
	s_mov_b32 m0, s89
	s_nop 0
	buffer_load_dwordx4 v221, s[20:23], s8 offen lds
	s_waitcnt vmcnt(24)
	s_waitcnt lgkmcnt(0)
	s_barrier
	s_setprio 1
	s_waitcnt lgkmcnt(7)
	v_mfma_f32_16x16x32_bf16 v[164:167], v[128:131], v[184:187], 0
	v_mfma_f32_16x16x32_bf16 v[160:163], v[152:155], v[184:187], 0
	s_waitcnt lgkmcnt(5)
	v_mfma_f32_16x16x32_bf16 v[136:139], v[128:131], v[192:195], 0
	v_mfma_f32_16x16x32_bf16 v[132:135], v[152:155], v[192:195], 0
	s_waitcnt lgkmcnt(3)
	v_mfma_f32_16x16x32_bf16 v[116:119], v[128:131], v[200:203], 0
	v_mfma_f32_16x16x32_bf16 v[112:115], v[152:155], v[200:203], 0
	s_waitcnt lgkmcnt(1)
	v_mfma_f32_16x16x32_bf16 v[76:79], v[128:131], v[224:227], 0
	v_mfma_f32_16x16x32_bf16 v[72:75], v[152:155], v[224:227], 0
	v_mfma_f32_16x16x32_bf16 v[164:167], v[140:143], v[188:191], v[164:167]
	v_mfma_f32_16x16x32_bf16 v[160:163], v[156:159], v[188:191], v[160:163]
	v_mfma_f32_16x16x32_bf16 v[136:139], v[140:143], v[196:199], v[136:139]
	v_mfma_f32_16x16x32_bf16 v[132:135], v[156:159], v[196:199], v[132:135]
	v_mfma_f32_16x16x32_bf16 v[116:119], v[140:143], v[204:207], v[116:119]
	v_mfma_f32_16x16x32_bf16 v[112:115], v[156:159], v[204:207], v[112:115]
	s_waitcnt lgkmcnt(0)
	v_mfma_f32_16x16x32_bf16 v[76:79], v[140:143], v[228:231], v[76:79]
	v_mfma_f32_16x16x32_bf16 v[72:75], v[156:159], v[228:231], v[72:75]
	s_setprio 0
	s_setprio 1
	v_mfma_f32_16x16x32_bf16 v[148:151], v[168:171], v[184:187], 0
	v_mfma_f32_16x16x32_bf16 v[144:147], v[176:179], v[184:187], 0
	v_mfma_f32_16x16x32_bf16 v[124:127], v[168:171], v[192:195], 0
	v_mfma_f32_16x16x32_bf16 v[120:123], v[176:179], v[192:195], 0
	v_mfma_f32_16x16x32_bf16 v[108:111], v[168:171], v[200:203], 0
	v_mfma_f32_16x16x32_bf16 v[104:107], v[176:179], v[200:203], 0
	v_mfma_f32_16x16x32_bf16 v[68:71], v[168:171], v[224:227], 0
	v_mfma_f32_16x16x32_bf16 v[64:67], v[176:179], v[224:227], 0
	v_mfma_f32_16x16x32_bf16 v[148:151], v[172:175], v[188:191], v[148:151]
	v_mfma_f32_16x16x32_bf16 v[144:147], v[180:183], v[188:191], v[144:147]
	v_mfma_f32_16x16x32_bf16 v[124:127], v[172:175], v[196:199], v[124:127]
	v_mfma_f32_16x16x32_bf16 v[120:123], v[180:183], v[196:199], v[120:123]
	v_mfma_f32_16x16x32_bf16 v[108:111], v[172:175], v[204:207], v[108:111]
	v_mfma_f32_16x16x32_bf16 v[104:107], v[180:183], v[204:207], v[104:107]
	v_mfma_f32_16x16x32_bf16 v[68:71], v[172:175], v[228:231], v[68:71]
	v_mfma_f32_16x16x32_bf16 v[64:67], v[180:183], v[228:231], v[64:67]
	s_setprio 0
	s_barrier
	ds_read_b128 v[184:187], v223 offset:16384
	ds_read_b128 v[188:191], v223 offset:17408
	ds_read_b128 v[192:195], v223 offset:18432
	ds_read_b128 v[196:199], v223 offset:19456
	ds_read_b128 v[200:203], v223 offset:20480
	ds_read_b128 v[204:207], v223 offset:21504
	ds_read_b128 v[224:227], v223 offset:22528
	ds_read_b128 v[228:231], v223 offset:23552
	s_mov_b32 m0, s51
	s_nop 0
	buffer_load_dwordx4 v220, s[52:55], s12 offen lds
	s_add_i32 s14, s12, 0x160000
	s_mov_b32 m0, s74
	s_nop 0
	buffer_load_dwordx4 v221, s[52:55], s12 offen lds
	s_nop 0
	s_mov_b32 m0, s75
	s_nop 0
	buffer_load_dwordx4 v220, s[52:55], s14 offen lds
	s_nop 0
	s_mov_b32 m0, s76
	s_nop 0
	buffer_load_dwordx4 v221, s[52:55], s14 offen lds
	s_nop 0
	s_mov_b32 m0, s31
	s_nop 0
	buffer_load_dwordx4 v220, s[20:23], s13 offen lds
	s_nop 0
	s_mov_b32 m0, s77
	s_nop 0
	buffer_load_dwordx4 v221, s[20:23], s13 offen lds
	s_waitcnt vmcnt(24)
	s_waitcnt lgkmcnt(0)
	s_barrier
	s_setprio 1
	s_waitcnt lgkmcnt(7)
	v_mfma_f32_16x16x32_bf16 v[60:63], v[128:131], v[184:187], 0
	v_mfma_f32_16x16x32_bf16 v[56:59], v[152:155], v[184:187], 0
	s_waitcnt lgkmcnt(5)
	v_mfma_f32_16x16x32_bf16 v[44:47], v[128:131], v[192:195], 0
	v_mfma_f32_16x16x32_bf16 v[40:43], v[152:155], v[192:195], 0
	s_waitcnt lgkmcnt(3)
	v_mfma_f32_16x16x32_bf16 v[28:31], v[128:131], v[200:203], 0
	v_mfma_f32_16x16x32_bf16 v[24:27], v[152:155], v[200:203], 0
	s_waitcnt lgkmcnt(1)
	v_mfma_f32_16x16x32_bf16 v[12:15], v[128:131], v[224:227], 0
	v_mfma_f32_16x16x32_bf16 v[8:11], v[152:155], v[224:227], 0
	v_mfma_f32_16x16x32_bf16 v[60:63], v[140:143], v[188:191], v[60:63]
	v_mfma_f32_16x16x32_bf16 v[56:59], v[156:159], v[188:191], v[56:59]
	v_mfma_f32_16x16x32_bf16 v[44:47], v[140:143], v[196:199], v[44:47]
	v_mfma_f32_16x16x32_bf16 v[40:43], v[156:159], v[196:199], v[40:43]
	v_mfma_f32_16x16x32_bf16 v[28:31], v[140:143], v[204:207], v[28:31]
	v_mfma_f32_16x16x32_bf16 v[24:27], v[156:159], v[204:207], v[24:27]
	s_waitcnt lgkmcnt(0)
	v_mfma_f32_16x16x32_bf16 v[12:15], v[140:143], v[228:231], v[12:15]
	v_mfma_f32_16x16x32_bf16 v[8:11], v[156:159], v[228:231], v[8:11]
	s_setprio 0
	s_setprio 1
	v_mfma_f32_16x16x32_bf16 v[52:55], v[168:171], v[184:187], 0
	v_mfma_f32_16x16x32_bf16 v[48:51], v[176:179], v[184:187], 0
	v_mfma_f32_16x16x32_bf16 v[36:39], v[168:171], v[192:195], 0
	v_mfma_f32_16x16x32_bf16 v[32:35], v[176:179], v[192:195], 0
	v_mfma_f32_16x16x32_bf16 v[20:23], v[168:171], v[200:203], 0
	v_mfma_f32_16x16x32_bf16 v[16:19], v[176:179], v[200:203], 0
	v_mfma_f32_16x16x32_bf16 v[4:7], v[168:171], v[224:227], 0
	v_mfma_f32_16x16x32_bf16 v[0:3], v[176:179], v[224:227], 0
	v_mfma_f32_16x16x32_bf16 v[52:55], v[172:175], v[188:191], v[52:55]
	v_mfma_f32_16x16x32_bf16 v[48:51], v[180:183], v[188:191], v[48:51]
	v_mfma_f32_16x16x32_bf16 v[36:39], v[172:175], v[196:199], v[36:39]
	v_mfma_f32_16x16x32_bf16 v[32:35], v[180:183], v[196:199], v[32:35]
	v_mfma_f32_16x16x32_bf16 v[20:23], v[172:175], v[204:207], v[20:23]
	v_mfma_f32_16x16x32_bf16 v[16:19], v[180:183], v[204:207], v[16:19]
	v_mfma_f32_16x16x32_bf16 v[4:7], v[172:175], v[228:231], v[4:7]
	v_mfma_f32_16x16x32_bf16 v[0:3], v[180:183], v[228:231], v[0:3]
	s_setprio 0
	s_barrier
	v_add_u32_e32 v156, 0x18000, v222
	v_add_u32_e32 v180, 0x1c000, v222
	ds_read_b128 v[128:131], v156
	ds_read_b128 v[140:143], v156 offset:1024
	ds_read_b128 v[152:155], v156 offset:2048
	ds_read_b128 v[156:159], v156 offset:3072
	ds_read_b128 v[168:171], v180
	ds_read_b128 v[172:175], v180 offset:1024
	ds_read_b128 v[176:179], v180 offset:2048
	ds_read_b128 v[180:183], v180 offset:3072
	ds_read_b128 v[184:187], v223 offset:32768
	ds_read_b128 v[188:191], v223 offset:33792
	ds_read_b128 v[192:195], v223 offset:34816
	ds_read_b128 v[196:199], v223 offset:35840
	ds_read_b128 v[200:203], v223 offset:36864
	ds_read_b128 v[204:207], v223 offset:37888
	ds_read_b128 v[224:227], v223 offset:38912
	ds_read_b128 v[228:231], v223 offset:39936
	s_add_i32 s13, s13, 0x160000
	s_mov_b32 m0, s78
	s_nop 0
	buffer_load_dwordx4 v220, s[20:23], s13 offen lds
	s_nop 0
	s_mov_b32 m0, s79
	s_nop 0
	buffer_load_dwordx4 v221, s[20:23], s13 offen lds
	s_waitcnt vmcnt(8)
	s_waitcnt lgkmcnt(0)
	s_barrier
	s_setprio 1
	s_waitcnt lgkmcnt(7)
	v_mfma_f32_16x16x32_bf16 v[164:167], v[128:131], v[184:187], v[164:167]
	v_mfma_f32_16x16x32_bf16 v[160:163], v[152:155], v[184:187], v[160:163]
	s_waitcnt lgkmcnt(5)
	v_mfma_f32_16x16x32_bf16 v[136:139], v[128:131], v[192:195], v[136:139]
	v_mfma_f32_16x16x32_bf16 v[132:135], v[152:155], v[192:195], v[132:135]
	s_waitcnt lgkmcnt(3)
	v_mfma_f32_16x16x32_bf16 v[116:119], v[128:131], v[200:203], v[116:119]
	v_mfma_f32_16x16x32_bf16 v[112:115], v[152:155], v[200:203], v[112:115]
	s_waitcnt lgkmcnt(1)
	v_mfma_f32_16x16x32_bf16 v[76:79], v[128:131], v[224:227], v[76:79]
	v_mfma_f32_16x16x32_bf16 v[72:75], v[152:155], v[224:227], v[72:75]
	v_mfma_f32_16x16x32_bf16 v[164:167], v[140:143], v[188:191], v[164:167]
	v_mfma_f32_16x16x32_bf16 v[160:163], v[156:159], v[188:191], v[160:163]
	v_mfma_f32_16x16x32_bf16 v[136:139], v[140:143], v[196:199], v[136:139]
	v_mfma_f32_16x16x32_bf16 v[132:135], v[156:159], v[196:199], v[132:135]
	v_mfma_f32_16x16x32_bf16 v[116:119], v[140:143], v[204:207], v[116:119]
	v_mfma_f32_16x16x32_bf16 v[112:115], v[156:159], v[204:207], v[112:115]
	s_waitcnt lgkmcnt(0)
	v_mfma_f32_16x16x32_bf16 v[76:79], v[140:143], v[228:231], v[76:79]
	v_mfma_f32_16x16x32_bf16 v[72:75], v[156:159], v[228:231], v[72:75]
	s_setprio 0
	s_setprio 1
	v_mfma_f32_16x16x32_bf16 v[148:151], v[168:171], v[184:187], v[148:151]
	v_mfma_f32_16x16x32_bf16 v[144:147], v[176:179], v[184:187], v[144:147]
	v_mfma_f32_16x16x32_bf16 v[124:127], v[168:171], v[192:195], v[124:127]
	v_mfma_f32_16x16x32_bf16 v[120:123], v[176:179], v[192:195], v[120:123]
	v_mfma_f32_16x16x32_bf16 v[108:111], v[168:171], v[200:203], v[108:111]
	v_mfma_f32_16x16x32_bf16 v[104:107], v[176:179], v[200:203], v[104:107]
	v_mfma_f32_16x16x32_bf16 v[68:71], v[168:171], v[224:227], v[68:71]
	v_mfma_f32_16x16x32_bf16 v[64:67], v[176:179], v[224:227], v[64:67]
	v_mfma_f32_16x16x32_bf16 v[148:151], v[172:175], v[188:191], v[148:151]
	v_mfma_f32_16x16x32_bf16 v[144:147], v[180:183], v[188:191], v[144:147]
	v_mfma_f32_16x16x32_bf16 v[124:127], v[172:175], v[196:199], v[124:127]
	v_mfma_f32_16x16x32_bf16 v[120:123], v[180:183], v[196:199], v[120:123]
	v_mfma_f32_16x16x32_bf16 v[108:111], v[172:175], v[204:207], v[108:111]
	v_mfma_f32_16x16x32_bf16 v[104:107], v[180:183], v[204:207], v[104:107]
	v_mfma_f32_16x16x32_bf16 v[68:71], v[172:175], v[228:231], v[68:71]
	v_mfma_f32_16x16x32_bf16 v[64:67], v[180:183], v[228:231], v[64:67]
	s_setprio 0
	s_barrier
	ds_read_b128 v[184:187], v223 offset:49152
	ds_read_b128 v[188:191], v223 offset:50176
	ds_read_b128 v[192:195], v223 offset:51200
	ds_read_b128 v[196:199], v223 offset:52224
	ds_read_b128 v[200:203], v223 offset:53248
	ds_read_b128 v[204:207], v223 offset:54272
	ds_read_b128 v[224:227], v223 offset:55296
	ds_read_b128 v[228:231], v223 offset:56320
	s_or_b32 s13, s12, 0x4000
	s_mov_b32 m0, s34
	s_nop 0
	buffer_load_dwordx4 v220, s[52:55], s13 offen lds
	s_add_i32 s12, s12, 0x164000
	s_mov_b32 m0, s82
	s_nop 0
	buffer_load_dwordx4 v221, s[52:55], s13 offen lds
	s_nop 0
	s_mov_b32 m0, s85
	s_nop 0
	buffer_load_dwordx4 v220, s[52:55], s12 offen lds
	s_nop 0
	s_mov_b32 m0, s86
	s_nop 0
	buffer_load_dwordx4 v221, s[52:55], s12 offen lds
	s_nop 0
	s_mov_b32 m0, s83
	s_nop 0
	buffer_load_dwordx4 v220, s[20:23], s11 offen lds
	s_nop 0
	s_mov_b32 m0, s84
	s_nop 0
	buffer_load_dwordx4 v221, s[20:23], s11 offen lds
	s_waitcnt vmcnt(8)
	s_waitcnt lgkmcnt(0)
	s_barrier
	s_setprio 1
	s_waitcnt lgkmcnt(7)
	v_mfma_f32_16x16x32_bf16 v[60:63], v[128:131], v[184:187], v[60:63]
	v_mfma_f32_16x16x32_bf16 v[56:59], v[152:155], v[184:187], v[56:59]
	s_waitcnt lgkmcnt(5)
	v_mfma_f32_16x16x32_bf16 v[44:47], v[128:131], v[192:195], v[44:47]
	v_mfma_f32_16x16x32_bf16 v[40:43], v[152:155], v[192:195], v[40:43]
	s_waitcnt lgkmcnt(3)
	v_mfma_f32_16x16x32_bf16 v[28:31], v[128:131], v[200:203], v[28:31]
	v_mfma_f32_16x16x32_bf16 v[24:27], v[152:155], v[200:203], v[24:27]
	s_waitcnt lgkmcnt(1)
	v_mfma_f32_16x16x32_bf16 v[12:15], v[128:131], v[224:227], v[12:15]
	v_mfma_f32_16x16x32_bf16 v[8:11], v[152:155], v[224:227], v[8:11]
	v_mfma_f32_16x16x32_bf16 v[60:63], v[140:143], v[188:191], v[60:63]
	v_mfma_f32_16x16x32_bf16 v[56:59], v[156:159], v[188:191], v[56:59]
	v_mfma_f32_16x16x32_bf16 v[44:47], v[140:143], v[196:199], v[44:47]
	v_mfma_f32_16x16x32_bf16 v[40:43], v[156:159], v[196:199], v[40:43]
	v_mfma_f32_16x16x32_bf16 v[28:31], v[140:143], v[204:207], v[28:31]
	v_mfma_f32_16x16x32_bf16 v[24:27], v[156:159], v[204:207], v[24:27]
	s_waitcnt lgkmcnt(0)
	v_mfma_f32_16x16x32_bf16 v[12:15], v[140:143], v[228:231], v[12:15]
	v_mfma_f32_16x16x32_bf16 v[8:11], v[156:159], v[228:231], v[8:11]
	s_setprio 0
	s_setprio 1
	v_mfma_f32_16x16x32_bf16 v[52:55], v[168:171], v[184:187], v[52:55]
	v_mfma_f32_16x16x32_bf16 v[48:51], v[176:179], v[184:187], v[48:51]
	v_mfma_f32_16x16x32_bf16 v[36:39], v[168:171], v[192:195], v[36:39]
	v_mfma_f32_16x16x32_bf16 v[32:35], v[176:179], v[192:195], v[32:35]
	v_mfma_f32_16x16x32_bf16 v[20:23], v[168:171], v[200:203], v[20:23]
	v_mfma_f32_16x16x32_bf16 v[16:19], v[176:179], v[200:203], v[16:19]
	v_mfma_f32_16x16x32_bf16 v[4:7], v[168:171], v[224:227], v[4:7]
	v_mfma_f32_16x16x32_bf16 v[0:3], v[176:179], v[224:227], v[0:3]
	v_mfma_f32_16x16x32_bf16 v[52:55], v[172:175], v[188:191], v[52:55]
	v_mfma_f32_16x16x32_bf16 v[48:51], v[180:183], v[188:191], v[48:51]
	v_mfma_f32_16x16x32_bf16 v[36:39], v[172:175], v[196:199], v[36:39]
	v_mfma_f32_16x16x32_bf16 v[32:35], v[180:183], v[196:199], v[32:35]
	v_mfma_f32_16x16x32_bf16 v[20:23], v[172:175], v[204:207], v[20:23]
	v_mfma_f32_16x16x32_bf16 v[16:19], v[180:183], v[204:207], v[16:19]
	v_mfma_f32_16x16x32_bf16 v[4:7], v[172:175], v[228:231], v[4:7]
	v_mfma_f32_16x16x32_bf16 v[0:3], v[180:183], v[228:231], v[0:3]
	s_setprio 0
	s_barrier
	s_add_i32 s10, s10, 2
	s_add_i32 s8, s8, 0x8000
	s_add_i32 s9, s9, 0x8000

.LBB0_904:
	s_or_b64 exec, exec, s[4:5]
	s_andn2_b64 vcc, exec, s[38:39]
	s_mov_b64 s[4:5], -1
	s_cbranch_vccnz .LBB0_877
	s_mov_b32 s101, 0
	s_andn2_b64 vcc, exec, s[0:1]
	s_cbranch_vccnz .LBB0_876
	s_mov_b32 s101, 1
	s_branch .LBB0_876
